# peer_down/peer_ffn: expert ids and coefs fetched once per token (coalesced) and staged through LDS instead of 16 per-row dword loads
# speedup vs baseline: 1.1098x; 1.0182x over previous
; DI float bflo(unsigned u) { return __uint_as_float(u << 16); }
; DI float bfhi(unsigned u) { return __uint_as_float(u & 0xffff0000u); }
; DI void phase_peer_down(const Params& p) {
;     ...
;   for (int tok = gw; tok < T_; tok += nw) {
;     float x[16];
;     {
;       const u16* xr = hb + (size_t)tok * 1024 + lane * 16;
;       u32x4 a = *reinterpret_cast<const u32x4*>(xr);
;       u32x4 c = *reinterpret_cast<const u32x4*>(xr + 8);
; #pragma unroll
;       for (int w = 0; w < 4; ++w) { x[2 * w] = bflo(a[w]); x[2 * w + 1] = bfhi(a[w]); x[8 + 2 * w] = bflo(c[w]); x[8 + 2 * w + 1] = bfhi(c[w]); }
;     }
; #pragma unroll 1
;     for (int half = 0; half < 2; ++half) {
;       const size_t slot = (size_t)tok * 128 + half * 64 + lane;
;       const int ev = eidx[slot];
;       const float gv = gate[slot];
;       float racc = 0.f, gacc = 0.f;
; #pragma unroll 1
;       for (int bi = 0; bi < 8; ++bi) {
;         u32x4 dr[8];
; #pragma unroll
;         for (int k = 0; k < 8; ++k) {
;           const int er = __builtin_amdgcn_readlane(ev, bi * 8 + k);
;           dr[k] = *reinterpret_cast<const u32x4*>(exd + (size_t)er * 1024 + lane * 16);
.LBB0_1022:
	s_or_b64 exec, exec, s[0:1]
	s_add_u32 s0, s96, 0x2000000
	s_mov_b32 s2, 0x200000
	s_addc_u32 s1, s97, 0
	s_lshr_b32 s33, s20, 6
	v_cmp_gt_u32_e64 s[2:3], s2, v140
	v_lshrrev_b32_e32 v64, 6, v140
	s_waitcnt lgkmcnt(0)
	s_barrier
	s_and_saveexec_b64 s[10:11], s[2:3]
	s_cbranch_execz .LBB0_1033
	s_mov_b32 s4, s96
	s_mov_b32 s5, s97
	s_add_u32 s6, s96, 0x4000000
	s_addc_u32 s7, s97, 0
	s_add_u32 s8, s96, 0x12800000
	s_addc_u32 s9, s97, 0
	s_add_u32 s12, s96, 0xa500000
	s_addc_u32 s13, s97, 0
	s_add_u32 s14, s96, 0x1000000
	s_addc_u32 s15, s97, 0
	s_add_u32 s16, s96, 0x2000000
	s_addc_u32 s17, s97, 0
	s_add_u32 s34, s96, 0xa510000
	s_addc_u32 s35, s97, 0
	v_and_b32_e32 v0, 63, v166
	v_lshrrev_b32_e32 v1, 3, v0
	v_lshlrev_b32_e32 v1, 2, v1
	v_and_b32_e32 v2, 7, v0
	v_cmp_eq_u32_e32 vcc, 0, v2
	s_nop 1
	v_cndmask_b32_e64 v12, 0, 1.0, vcc
	v_cmp_eq_u32_e32 vcc, 1, v2
	s_nop 1
	v_cndmask_b32_e64 v13, 0, 1.0, vcc
	v_cmp_eq_u32_e32 vcc, 2, v2
	s_nop 1
	v_cndmask_b32_e64 v14, 0, 1.0, vcc
	v_cmp_eq_u32_e32 vcc, 3, v2
	s_nop 1
	v_cndmask_b32_e64 v15, 0, 1.0, vcc
	v_cmp_eq_u32_e32 vcc, 4, v2
	s_nop 1
	v_cndmask_b32_e64 v16, 0, 1.0, vcc
	v_cmp_eq_u32_e32 vcc, 5, v2
	s_nop 1
	v_cndmask_b32_e64 v17, 0, 1.0, vcc
	v_cmp_eq_u32_e32 vcc, 6, v2
	s_nop 1
	v_cndmask_b32_e64 v18, 0, 1.0, vcc
	v_cmp_eq_u32_e32 vcc, 7, v2
	s_nop 1
	v_cndmask_b32_e64 v19, 0, 1.0, vcc
	v_lshlrev_b32_e32 v3, 5, v2
	v_lshlrev_b32_e32 v2, 4, v2
	v_lshrrev_b32_e32 v4, 6, v166
	v_lshlrev_b32_e32 v4, 13, v4
	v_lshl_add_u32 v4, v0, 3, v4
	v_mov_b32_e32 v98, 0
	v_mov_b32_e32 v99, 0
	ds_write_b64 v4, v[98:99] offset:0
	ds_write_b64 v4, v[98:99] offset:512
	ds_write_b64 v4, v[98:99] offset:1024
	ds_write_b64 v4, v[98:99] offset:1536
	ds_write_b64 v4, v[98:99] offset:2048
	ds_write_b64 v4, v[98:99] offset:2560
	ds_write_b64 v4, v[98:99] offset:3072
	ds_write_b64 v4, v[98:99] offset:3584
	ds_write_b64 v4, v[98:99] offset:4096
	ds_write_b64 v4, v[98:99] offset:4608
	ds_write_b64 v4, v[98:99] offset:5120
	ds_write_b64 v4, v[98:99] offset:5632
	ds_write_b64 v4, v[98:99] offset:6144
	ds_write_b64 v4, v[98:99] offset:6656
	ds_write_b64 v4, v[98:99] offset:7168
	ds_write_b64 v4, v[98:99] offset:7680
	v_lshl_add_u32 v7, v64, 11, v3
	global_load_dwordx4 v[20:23], v7, s[8:9]
	global_load_dwordx4 v[24:27], v7, s[8:9] offset:16
	v_lshlrev_b32_e32 v212, 3, v0
	v_lshrrev_b32_e32 v213, 6, v166
	v_lshlrev_b32_e32 v213, 9, v213
	v_add_u32_e32 v213, 0x10000, v213
	v_lshl_add_u32 v214, v1, 4, v213
	v_add_u32_e32 v213, v212, v213
	v_lshl_add_u32 v9, v64, 9, v212
	global_load_dwordx2 v[216:217], v9, s[4:5]
	s_waitcnt vmcnt(0)
	ds_write_b64 v213, v[216:217]
	ds_read_b128 v[100:103], v214 offset:0
	ds_read_b128 v[104:107], v214 offset:16
	ds_read_b128 v[108:111], v214 offset:32
	ds_read_b128 v[112:115], v214 offset:48
	v_add_u32_e32 v5, 0x800, v64
	v_lshl_add_u32 v9, v5, 9, v212
	global_load_dwordx2 v[216:217], v9, s[4:5]
	s_waitcnt lgkmcnt(0)
	v_lshl_add_u32 v11, v100, 10, v2
	global_load_dwordx4 v[116:119], v11, s[6:7]
	v_lshl_add_u32 v11, v101, 10, v2
	global_load_dwordx4 v[120:123], v11, s[6:7]
	v_lshl_add_u32 v11, v102, 10, v2
	global_load_dwordx4 v[124:127], v11, s[6:7]
	v_lshl_add_u32 v11, v103, 10, v2
	global_load_dwordx4 v[128:131], v11, s[6:7]
	v_lshl_add_u32 v11, v104, 10, v2
	global_load_dwordx4 v[132:135], v11, s[6:7]
	v_lshl_add_u32 v11, v105, 10, v2
	global_load_dwordx4 v[136:139], v11, s[6:7]
	v_lshl_add_u32 v11, v106, 10, v2
	global_load_dwordx4 v[140:143], v11, s[6:7]
	v_lshl_add_u32 v11, v107, 10, v2
	global_load_dwordx4 v[144:147], v11, s[6:7]
	v_lshl_add_u32 v11, v108, 10, v2
	global_load_dwordx4 v[180:183], v11, s[6:7]
	v_lshl_add_u32 v11, v109, 10, v2
	global_load_dwordx4 v[184:187], v11, s[6:7]
	v_lshl_add_u32 v11, v110, 10, v2
	global_load_dwordx4 v[188:191], v11, s[6:7]
	v_lshl_add_u32 v11, v111, 10, v2
	global_load_dwordx4 v[192:195], v11, s[6:7]
	v_lshl_add_u32 v11, v112, 10, v2
	global_load_dwordx4 v[196:199], v11, s[6:7]
	v_lshl_add_u32 v11, v113, 10, v2
	global_load_dwordx4 v[200:203], v11, s[6:7]
	v_lshl_add_u32 v11, v114, 10, v2
	global_load_dwordx4 v[204:207], v11, s[6:7]
	v_lshl_add_u32 v11, v115, 10, v2
	global_load_dwordx4 v[208:211], v11, s[6:7]
	s_mov_b32 s18, 0
	s_waitcnt lgkmcnt(0)
; DI void phase_peer_down(const Params& p) {
;     ...
; #pragma unroll 1
;       for (int bi = 0; bi < 8; ++bi) {
;         u32x4 dr[8];
; #pragma unroll
;         for (int k = 0; k < 8; ++k) {
;           const int er = __builtin_amdgcn_readlane(ev, bi * 8 + k);
;           dr[k] = *reinterpret_cast<const u32x4*>(exd + (size_t)er * 1024 + lane * 16);
;         }
;         const int pmine = bi * 8 + (lane & 7);
;         const int emine = __shfl(ev, pmine);
;         const float gsel = __shfl(gv, pmine);
;         const float sd = esc[emine];
;         const float su = esc[16384 + emine];
;         float part[8];
; #pragma unroll
;         for (int k = 0; k < 8; ++k) {
;           float a0 = 0.f, a1 = 0.f;
; #pragma unroll
;           for (int w = 0; w < 4; ++w) {
;             f2_t lo = __builtin_amdgcn_cvt_pk_f32_fp8((int)dr[k][w], false);
;             f2_t hi = __builtin_amdgcn_cvt_pk_f32_fp8((int)dr[k][w], true);
;             a0 = fmaf(lo[0], x[4 * w], a0); a1 = fmaf(lo[1], x[4 * w + 1], a1);
;             a0 = fmaf(hi[0], x[4 * w + 2], a0); a1 = fmaf(hi[1], x[4 * w + 3], a1);
;           }
;           part[k] = a0 + a1;
;         }
;         const float r1 = reduce8(part, lane) * sd;
;         const bool mine = (lane >> 3) == bi;
;         racc = mine ? r1 : racc; gacc = mine ? gsel * su : gacc;
;       }
.Lpd_loop:
	s_add_i32 s20, s18, 1
	s_min_i32 s20, s20, 0x7f
	s_lshr_b32 s21, s20, 4
	s_and_b32 s22, s20, 15
	s_add_i32 s23, s18, 2
	s_min_i32 s23, s23, 0x7f
	s_and_b32 s24, s23, 15
	s_and_b32 s26, s18, 15
	s_lshl_b32 s22, s22, 11
	s_lshl_b32 s24, s24, 11
	s_lshl_b32 s27, s21, 8
	s_lshl_b32 s28, s21, 7
	s_lshl_b32 s29, s26, 9
	v_add_u32_e32 v5, s22, v64
	v_add_u32_e32 v6, s24, v64
	v_add_u32_e32 v10, s29, v4
	v_lshl_add_u32 v7, v5, 11, v3
	v_add_u32_e32 v7, s27, v7
	v_add_u32_e32 v8, s28, v2
	v_lshl_add_u32 v9, v6, 9, v212
	ds_read_b64 v[98:99], v10
	s_waitcnt vmcnt(16)
	v_lshlrev_b32_e32 v28, 16, v20
	v_and_b32_e32 v29, 0xffff0000, v20
	v_lshlrev_b32_e32 v30, 16, v21
	v_and_b32_e32 v31, 0xffff0000, v21
	v_lshlrev_b32_e32 v32, 16, v22
	v_and_b32_e32 v33, 0xffff0000, v22
	v_lshlrev_b32_e32 v34, 16, v23
	v_and_b32_e32 v35, 0xffff0000, v23
	v_lshlrev_b32_e32 v36, 16, v24
	v_and_b32_e32 v37, 0xffff0000, v24
	v_lshlrev_b32_e32 v38, 16, v25
	v_and_b32_e32 v39, 0xffff0000, v25
	v_lshlrev_b32_e32 v40, 16, v26
	v_and_b32_e32 v41, 0xffff0000, v26
	v_lshlrev_b32_e32 v42, 16, v27
	v_and_b32_e32 v43, 0xffff0000, v27
	global_load_dwordx4 v[20:23], v7, s[8:9]
	global_load_dwordx4 v[24:27], v7, s[8:9] offset:16
	ds_write_b64 v213, v[216:217]
	ds_read_b128 v[100:103], v214 offset:0
	ds_read_b128 v[104:107], v214 offset:16
	ds_read_b128 v[108:111], v214 offset:32
	ds_read_b128 v[112:115], v214 offset:48
	global_load_dwordx2 v[216:217], v9, s[4:5]
	s_waitcnt lgkmcnt(0)
	s_waitcnt vmcnt(17)
	v_cvt_pk_f32_fp8_e32 v[44:45], v116
	v_cvt_pk_f32_fp8_sdwa v[46:47], v116 src0_sel:WORD_1
	v_cvt_pk_f32_fp8_e32 v[48:49], v117
	v_cvt_pk_f32_fp8_sdwa v[50:51], v117 src0_sel:WORD_1
	v_cvt_pk_f32_fp8_e32 v[52:53], v118
	v_cvt_pk_f32_fp8_sdwa v[54:55], v118 src0_sel:WORD_1
	v_cvt_pk_f32_fp8_e32 v[56:57], v119
	v_cvt_pk_f32_fp8_sdwa v[58:59], v119 src0_sel:WORD_1
	v_cvt_pk_f32_fp8_e32 v[66:67], v120
	v_cvt_pk_f32_fp8_sdwa v[68:69], v120 src0_sel:WORD_1
	v_cvt_pk_f32_fp8_e32 v[70:71], v121
	v_cvt_pk_f32_fp8_sdwa v[72:73], v121 src0_sel:WORD_1
	v_cvt_pk_f32_fp8_e32 v[74:75], v122
	v_cvt_pk_f32_fp8_sdwa v[76:77], v122 src0_sel:WORD_1
	v_cvt_pk_f32_fp8_e32 v[78:79], v123
	v_cvt_pk_f32_fp8_sdwa v[80:81], v123 src0_sel:WORD_1
	v_pk_mul_f32 v[82:83], v[44:45], v[28:29]
	v_pk_mul_f32 v[86:87], v[66:67], v[28:29]
	v_pk_mul_f32 v[84:85], v[46:47], v[30:31]
	v_pk_mul_f32 v[88:89], v[68:69], v[30:31]
	v_pk_fma_f32 v[82:83], v[48:49], v[32:33], v[82:83]
	v_pk_fma_f32 v[86:87], v[70:71], v[32:33], v[86:87]
	v_pk_fma_f32 v[84:85], v[50:51], v[34:35], v[84:85]
	v_pk_fma_f32 v[88:89], v[72:73], v[34:35], v[88:89]
	v_pk_fma_f32 v[82:83], v[52:53], v[36:37], v[82:83]
	v_pk_fma_f32 v[86:87], v[74:75], v[36:37], v[86:87]
	v_pk_fma_f32 v[84:85], v[54:55], v[38:39], v[84:85]
	v_pk_fma_f32 v[88:89], v[76:77], v[38:39], v[88:89]
	v_pk_fma_f32 v[82:83], v[56:57], v[40:41], v[82:83]
	v_pk_fma_f32 v[86:87], v[78:79], v[40:41], v[86:87]
	v_pk_fma_f32 v[84:85], v[58:59], v[42:43], v[84:85]
	v_pk_fma_f32 v[88:89], v[80:81], v[42:43], v[88:89]
	v_pk_add_f32 v[82:83], v[82:83], v[84:85]
	v_pk_add_f32 v[86:87], v[86:87], v[88:89]
	v_lshl_add_u32 v11, v100, 10, v8
	v_add_f32_e32 v90, v82, v83
	v_add_f32_e32 v94, v86, v87
	global_load_dwordx4 v[116:119], v11, s[6:7]
	v_lshl_add_u32 v65, v101, 10, v8
	v_add_f32_dpp v91, v90, v90 quad_perm:[1,0,3,2] row_mask:0xf bank_mask:0xf
	v_add_f32_dpp v95, v94, v94 quad_perm:[1,0,3,2] row_mask:0xf bank_mask:0xf
	global_load_dwordx4 v[120:123], v65, s[6:7]
	v_add_f32_dpp v92, v91, v91 quad_perm:[2,3,0,1] row_mask:0xf bank_mask:0xf
	v_add_f32_dpp v96, v95, v95 quad_perm:[2,3,0,1] row_mask:0xf bank_mask:0xf
	s_nop 0
	v_add_f32_dpp v93, v92, v92 row_half_mirror row_mask:0xf bank_mask:0xf
	v_add_f32_dpp v97, v96, v96 row_half_mirror row_mask:0xf bank_mask:0xf
	v_fmac_f32_e32 v98, v93, v12
	v_fmac_f32_e32 v98, v97, v13
	s_waitcnt vmcnt(17)
	v_cvt_pk_f32_fp8_e32 v[44:45], v124
	v_cvt_pk_f32_fp8_sdwa v[46:47], v124 src0_sel:WORD_1
	v_cvt_pk_f32_fp8_e32 v[48:49], v125
	v_cvt_pk_f32_fp8_sdwa v[50:51], v125 src0_sel:WORD_1
	v_cvt_pk_f32_fp8_e32 v[52:53], v126
	v_cvt_pk_f32_fp8_sdwa v[54:55], v126 src0_sel:WORD_1
	v_cvt_pk_f32_fp8_e32 v[56:57], v127
	v_cvt_pk_f32_fp8_sdwa v[58:59], v127 src0_sel:WORD_1
	v_cvt_pk_f32_fp8_e32 v[66:67], v128
	v_cvt_pk_f32_fp8_sdwa v[68:69], v128 src0_sel:WORD_1
	v_cvt_pk_f32_fp8_e32 v[70:71], v129
	v_cvt_pk_f32_fp8_sdwa v[72:73], v129 src0_sel:WORD_1
	v_cvt_pk_f32_fp8_e32 v[74:75], v130
	v_cvt_pk_f32_fp8_sdwa v[76:77], v130 src0_sel:WORD_1
	v_cvt_pk_f32_fp8_e32 v[78:79], v131
	v_cvt_pk_f32_fp8_sdwa v[80:81], v131 src0_sel:WORD_1
	v_pk_mul_f32 v[82:83], v[44:45], v[28:29]
	v_pk_mul_f32 v[86:87], v[66:67], v[28:29]
	v_pk_mul_f32 v[84:85], v[46:47], v[30:31]
	v_pk_mul_f32 v[88:89], v[68:69], v[30:31]
	v_pk_fma_f32 v[82:83], v[48:49], v[32:33], v[82:83]
	v_pk_fma_f32 v[86:87], v[70:71], v[32:33], v[86:87]
	v_pk_fma_f32 v[84:85], v[50:51], v[34:35], v[84:85]
	v_pk_fma_f32 v[88:89], v[72:73], v[34:35], v[88:89]
	v_pk_fma_f32 v[82:83], v[52:53], v[36:37], v[82:83]
	v_pk_fma_f32 v[86:87], v[74:75], v[36:37], v[86:87]
	v_pk_fma_f32 v[84:85], v[54:55], v[38:39], v[84:85]
	v_pk_fma_f32 v[88:89], v[76:77], v[38:39], v[88:89]
	v_pk_fma_f32 v[82:83], v[56:57], v[40:41], v[82:83]
	v_pk_fma_f32 v[86:87], v[78:79], v[40:41], v[86:87]
	v_pk_fma_f32 v[84:85], v[58:59], v[42:43], v[84:85]
	v_pk_fma_f32 v[88:89], v[80:81], v[42:43], v[88:89]
	v_pk_add_f32 v[82:83], v[82:83], v[84:85]
	v_pk_add_f32 v[86:87], v[86:87], v[88:89]
	v_lshl_add_u32 v11, v102, 10, v8
	v_add_f32_e32 v90, v82, v83
	v_add_f32_e32 v94, v86, v87
	global_load_dwordx4 v[124:127], v11, s[6:7]
	v_lshl_add_u32 v65, v103, 10, v8
	v_add_f32_dpp v91, v90, v90 quad_perm:[1,0,3,2] row_mask:0xf bank_mask:0xf
	v_add_f32_dpp v95, v94, v94 quad_perm:[1,0,3,2] row_mask:0xf bank_mask:0xf
	global_load_dwordx4 v[128:131], v65, s[6:7]
	v_add_f32_dpp v92, v91, v91 quad_perm:[2,3,0,1] row_mask:0xf bank_mask:0xf
	v_add_f32_dpp v96, v95, v95 quad_perm:[2,3,0,1] row_mask:0xf bank_mask:0xf
	s_nop 0
	v_add_f32_dpp v93, v92, v92 row_half_mirror row_mask:0xf bank_mask:0xf
	v_add_f32_dpp v97, v96, v96 row_half_mirror row_mask:0xf bank_mask:0xf
	v_fmac_f32_e32 v98, v93, v14
	v_fmac_f32_e32 v98, v97, v15
	s_waitcnt vmcnt(17)
; DI void phase_peer_down(const Params& p) {
;     ...
;       for (int bi = 0; bi < 8; ++bi) {
;         u32x4 dr[8];
; #pragma unroll
;         for (int k = 0; k < 8; ++k) {
;           const int er = __builtin_amdgcn_readlane(ev, bi * 8 + k);
;           dr[k] = *reinterpret_cast<const u32x4*>(exd + (size_t)er * 1024 + lane * 16);
;         }
;         const int pmine = bi * 8 + (lane & 7);
;         const int emine = __shfl(ev, pmine);
;         const float gsel = __shfl(gv, pmine);
;         const float sd = esc[emine];
;         const float su = esc[16384 + emine];
;         float part[8];
; #pragma unroll
;         for (int k = 0; k < 8; ++k) {
;           float a0 = 0.f, a1 = 0.f;
; #pragma unroll
;           for (int w = 0; w < 4; ++w) {
;             f2_t lo = __builtin_amdgcn_cvt_pk_f32_fp8((int)dr[k][w], false);
;             f2_t hi = __builtin_amdgcn_cvt_pk_f32_fp8((int)dr[k][w], true);
;             a0 = fmaf(lo[0], x[4 * w], a0); a1 = fmaf(lo[1], x[4 * w + 1], a1);
;             a0 = fmaf(hi[0], x[4 * w + 2], a0); a1 = fmaf(hi[1], x[4 * w + 3], a1);
;           }
;           part[k] = a0 + a1;
;         }
;         const float r1 = reduce8(part, lane) * sd;
;         const bool mine = (lane >> 3) == bi;
;         racc = mine ? r1 : racc; gacc = mine ? gsel * su : gacc;
;       }
	v_cvt_pk_f32_fp8_e32 v[44:45], v132
	v_cvt_pk_f32_fp8_sdwa v[46:47], v132 src0_sel:WORD_1
	v_cvt_pk_f32_fp8_e32 v[48:49], v133
	v_cvt_pk_f32_fp8_sdwa v[50:51], v133 src0_sel:WORD_1
	v_cvt_pk_f32_fp8_e32 v[52:53], v134
	v_cvt_pk_f32_fp8_sdwa v[54:55], v134 src0_sel:WORD_1
	v_cvt_pk_f32_fp8_e32 v[56:57], v135
	v_cvt_pk_f32_fp8_sdwa v[58:59], v135 src0_sel:WORD_1
	v_cvt_pk_f32_fp8_e32 v[66:67], v136
	v_cvt_pk_f32_fp8_sdwa v[68:69], v136 src0_sel:WORD_1
	v_cvt_pk_f32_fp8_e32 v[70:71], v137
	v_cvt_pk_f32_fp8_sdwa v[72:73], v137 src0_sel:WORD_1
	v_cvt_pk_f32_fp8_e32 v[74:75], v138
	v_cvt_pk_f32_fp8_sdwa v[76:77], v138 src0_sel:WORD_1
	v_cvt_pk_f32_fp8_e32 v[78:79], v139
	v_cvt_pk_f32_fp8_sdwa v[80:81], v139 src0_sel:WORD_1
	v_pk_mul_f32 v[82:83], v[44:45], v[28:29]
	v_pk_mul_f32 v[86:87], v[66:67], v[28:29]
	v_pk_mul_f32 v[84:85], v[46:47], v[30:31]
	v_pk_mul_f32 v[88:89], v[68:69], v[30:31]
	v_pk_fma_f32 v[82:83], v[48:49], v[32:33], v[82:83]
	v_pk_fma_f32 v[86:87], v[70:71], v[32:33], v[86:87]
	v_pk_fma_f32 v[84:85], v[50:51], v[34:35], v[84:85]
	v_pk_fma_f32 v[88:89], v[72:73], v[34:35], v[88:89]
	v_pk_fma_f32 v[82:83], v[52:53], v[36:37], v[82:83]
	v_pk_fma_f32 v[86:87], v[74:75], v[36:37], v[86:87]
	v_pk_fma_f32 v[84:85], v[54:55], v[38:39], v[84:85]
	v_pk_fma_f32 v[88:89], v[76:77], v[38:39], v[88:89]
	v_pk_fma_f32 v[82:83], v[56:57], v[40:41], v[82:83]
	v_pk_fma_f32 v[86:87], v[78:79], v[40:41], v[86:87]
	v_pk_fma_f32 v[84:85], v[58:59], v[42:43], v[84:85]
	v_pk_fma_f32 v[88:89], v[80:81], v[42:43], v[88:89]
	v_pk_add_f32 v[82:83], v[82:83], v[84:85]
	v_pk_add_f32 v[86:87], v[86:87], v[88:89]
	v_lshl_add_u32 v11, v104, 10, v8
	v_add_f32_e32 v90, v82, v83
	v_add_f32_e32 v94, v86, v87
	global_load_dwordx4 v[132:135], v11, s[6:7]
	v_lshl_add_u32 v65, v105, 10, v8
	v_add_f32_dpp v91, v90, v90 quad_perm:[1,0,3,2] row_mask:0xf bank_mask:0xf
	v_add_f32_dpp v95, v94, v94 quad_perm:[1,0,3,2] row_mask:0xf bank_mask:0xf
	global_load_dwordx4 v[136:139], v65, s[6:7]
	v_add_f32_dpp v92, v91, v91 quad_perm:[2,3,0,1] row_mask:0xf bank_mask:0xf
	v_add_f32_dpp v96, v95, v95 quad_perm:[2,3,0,1] row_mask:0xf bank_mask:0xf
	s_nop 0
	v_add_f32_dpp v93, v92, v92 row_half_mirror row_mask:0xf bank_mask:0xf
	v_add_f32_dpp v97, v96, v96 row_half_mirror row_mask:0xf bank_mask:0xf
	v_fmac_f32_e32 v98, v93, v16
	v_fmac_f32_e32 v98, v97, v17
	s_waitcnt vmcnt(17)
	v_cvt_pk_f32_fp8_e32 v[44:45], v140
	v_cvt_pk_f32_fp8_sdwa v[46:47], v140 src0_sel:WORD_1
	v_cvt_pk_f32_fp8_e32 v[48:49], v141
	v_cvt_pk_f32_fp8_sdwa v[50:51], v141 src0_sel:WORD_1
	v_cvt_pk_f32_fp8_e32 v[52:53], v142
	v_cvt_pk_f32_fp8_sdwa v[54:55], v142 src0_sel:WORD_1
	v_cvt_pk_f32_fp8_e32 v[56:57], v143
	v_cvt_pk_f32_fp8_sdwa v[58:59], v143 src0_sel:WORD_1
	v_cvt_pk_f32_fp8_e32 v[66:67], v144
	v_cvt_pk_f32_fp8_sdwa v[68:69], v144 src0_sel:WORD_1
	v_cvt_pk_f32_fp8_e32 v[70:71], v145
	v_cvt_pk_f32_fp8_sdwa v[72:73], v145 src0_sel:WORD_1
	v_cvt_pk_f32_fp8_e32 v[74:75], v146
	v_cvt_pk_f32_fp8_sdwa v[76:77], v146 src0_sel:WORD_1
	v_cvt_pk_f32_fp8_e32 v[78:79], v147
	v_cvt_pk_f32_fp8_sdwa v[80:81], v147 src0_sel:WORD_1
	v_pk_mul_f32 v[82:83], v[44:45], v[28:29]
	v_pk_mul_f32 v[86:87], v[66:67], v[28:29]
	v_pk_mul_f32 v[84:85], v[46:47], v[30:31]
	v_pk_mul_f32 v[88:89], v[68:69], v[30:31]
	v_pk_fma_f32 v[82:83], v[48:49], v[32:33], v[82:83]
	v_pk_fma_f32 v[86:87], v[70:71], v[32:33], v[86:87]
	v_pk_fma_f32 v[84:85], v[50:51], v[34:35], v[84:85]
	v_pk_fma_f32 v[88:89], v[72:73], v[34:35], v[88:89]
	v_pk_fma_f32 v[82:83], v[52:53], v[36:37], v[82:83]
	v_pk_fma_f32 v[86:87], v[74:75], v[36:37], v[86:87]
	v_pk_fma_f32 v[84:85], v[54:55], v[38:39], v[84:85]
	v_pk_fma_f32 v[88:89], v[76:77], v[38:39], v[88:89]
	v_pk_fma_f32 v[82:83], v[56:57], v[40:41], v[82:83]
	v_pk_fma_f32 v[86:87], v[78:79], v[40:41], v[86:87]
	v_pk_fma_f32 v[84:85], v[58:59], v[42:43], v[84:85]
	v_pk_fma_f32 v[88:89], v[80:81], v[42:43], v[88:89]
	v_pk_add_f32 v[82:83], v[82:83], v[84:85]
	v_pk_add_f32 v[86:87], v[86:87], v[88:89]
	v_lshl_add_u32 v11, v106, 10, v8
	v_add_f32_e32 v90, v82, v83
	v_add_f32_e32 v94, v86, v87
	global_load_dwordx4 v[140:143], v11, s[6:7]
	v_lshl_add_u32 v65, v107, 10, v8
	v_add_f32_dpp v91, v90, v90 quad_perm:[1,0,3,2] row_mask:0xf bank_mask:0xf
	v_add_f32_dpp v95, v94, v94 quad_perm:[1,0,3,2] row_mask:0xf bank_mask:0xf
	global_load_dwordx4 v[144:147], v65, s[6:7]
	v_add_f32_dpp v92, v91, v91 quad_perm:[2,3,0,1] row_mask:0xf bank_mask:0xf
	v_add_f32_dpp v96, v95, v95 quad_perm:[2,3,0,1] row_mask:0xf bank_mask:0xf
	s_nop 0
	v_add_f32_dpp v93, v92, v92 row_half_mirror row_mask:0xf bank_mask:0xf
	v_add_f32_dpp v97, v96, v96 row_half_mirror row_mask:0xf bank_mask:0xf
	v_fmac_f32_e32 v98, v93, v18
	v_fmac_f32_e32 v98, v97, v19
	s_waitcnt vmcnt(17)
; DI void phase_peer_down(const Params& p) {
;     ...
;       for (int bi = 0; bi < 8; ++bi) {
;         u32x4 dr[8];
; #pragma unroll
;         for (int k = 0; k < 8; ++k) {
;           const int er = __builtin_amdgcn_readlane(ev, bi * 8 + k);
;           dr[k] = *reinterpret_cast<const u32x4*>(exd + (size_t)er * 1024 + lane * 16);
;         }
;         const int pmine = bi * 8 + (lane & 7);
;         const int emine = __shfl(ev, pmine);
;         const float gsel = __shfl(gv, pmine);
;         const float sd = esc[emine];
;         const float su = esc[16384 + emine];
;         float part[8];
; #pragma unroll
;         for (int k = 0; k < 8; ++k) {
;           float a0 = 0.f, a1 = 0.f;
; #pragma unroll
;           for (int w = 0; w < 4; ++w) {
;             f2_t lo = __builtin_amdgcn_cvt_pk_f32_fp8((int)dr[k][w], false);
;             f2_t hi = __builtin_amdgcn_cvt_pk_f32_fp8((int)dr[k][w], true);
;             a0 = fmaf(lo[0], x[4 * w], a0); a1 = fmaf(lo[1], x[4 * w + 1], a1);
;             a0 = fmaf(hi[0], x[4 * w + 2], a0); a1 = fmaf(hi[1], x[4 * w + 3], a1);
;           }
;           part[k] = a0 + a1;
;         }
;         const float r1 = reduce8(part, lane) * sd;
;         const bool mine = (lane >> 3) == bi;
;         racc = mine ? r1 : racc; gacc = mine ? gsel * su : gacc;
;       }
	v_cvt_pk_f32_fp8_e32 v[44:45], v180
	v_cvt_pk_f32_fp8_sdwa v[46:47], v180 src0_sel:WORD_1
	v_cvt_pk_f32_fp8_e32 v[48:49], v181
	v_cvt_pk_f32_fp8_sdwa v[50:51], v181 src0_sel:WORD_1
	v_cvt_pk_f32_fp8_e32 v[52:53], v182
	v_cvt_pk_f32_fp8_sdwa v[54:55], v182 src0_sel:WORD_1
	v_cvt_pk_f32_fp8_e32 v[56:57], v183
	v_cvt_pk_f32_fp8_sdwa v[58:59], v183 src0_sel:WORD_1
	v_cvt_pk_f32_fp8_e32 v[66:67], v184
	v_cvt_pk_f32_fp8_sdwa v[68:69], v184 src0_sel:WORD_1
	v_cvt_pk_f32_fp8_e32 v[70:71], v185
	v_cvt_pk_f32_fp8_sdwa v[72:73], v185 src0_sel:WORD_1
	v_cvt_pk_f32_fp8_e32 v[74:75], v186
	v_cvt_pk_f32_fp8_sdwa v[76:77], v186 src0_sel:WORD_1
	v_cvt_pk_f32_fp8_e32 v[78:79], v187
	v_cvt_pk_f32_fp8_sdwa v[80:81], v187 src0_sel:WORD_1
	v_pk_mul_f32 v[82:83], v[44:45], v[28:29]
	v_pk_mul_f32 v[86:87], v[66:67], v[28:29]
	v_pk_mul_f32 v[84:85], v[46:47], v[30:31]
	v_pk_mul_f32 v[88:89], v[68:69], v[30:31]
	v_pk_fma_f32 v[82:83], v[48:49], v[32:33], v[82:83]
	v_pk_fma_f32 v[86:87], v[70:71], v[32:33], v[86:87]
	v_pk_fma_f32 v[84:85], v[50:51], v[34:35], v[84:85]
	v_pk_fma_f32 v[88:89], v[72:73], v[34:35], v[88:89]
	v_pk_fma_f32 v[82:83], v[52:53], v[36:37], v[82:83]
	v_pk_fma_f32 v[86:87], v[74:75], v[36:37], v[86:87]
	v_pk_fma_f32 v[84:85], v[54:55], v[38:39], v[84:85]
	v_pk_fma_f32 v[88:89], v[76:77], v[38:39], v[88:89]
	v_pk_fma_f32 v[82:83], v[56:57], v[40:41], v[82:83]
	v_pk_fma_f32 v[86:87], v[78:79], v[40:41], v[86:87]
	v_pk_fma_f32 v[84:85], v[58:59], v[42:43], v[84:85]
	v_pk_fma_f32 v[88:89], v[80:81], v[42:43], v[88:89]
	v_pk_add_f32 v[82:83], v[82:83], v[84:85]
	v_pk_add_f32 v[86:87], v[86:87], v[88:89]
	v_lshl_add_u32 v11, v108, 10, v8
	v_add_f32_e32 v90, v82, v83
	v_add_f32_e32 v94, v86, v87
	global_load_dwordx4 v[180:183], v11, s[6:7]
	v_lshl_add_u32 v65, v109, 10, v8
	v_add_f32_dpp v91, v90, v90 quad_perm:[1,0,3,2] row_mask:0xf bank_mask:0xf
	v_add_f32_dpp v95, v94, v94 quad_perm:[1,0,3,2] row_mask:0xf bank_mask:0xf
	global_load_dwordx4 v[184:187], v65, s[6:7]
	v_add_f32_dpp v92, v91, v91 quad_perm:[2,3,0,1] row_mask:0xf bank_mask:0xf
	v_add_f32_dpp v96, v95, v95 quad_perm:[2,3,0,1] row_mask:0xf bank_mask:0xf
	s_nop 0
	v_add_f32_dpp v93, v92, v92 row_half_mirror row_mask:0xf bank_mask:0xf
	v_add_f32_dpp v97, v96, v96 row_half_mirror row_mask:0xf bank_mask:0xf
	v_fmac_f32_e32 v99, v93, v12
	v_fmac_f32_e32 v99, v97, v13
	s_waitcnt vmcnt(17)
	v_cvt_pk_f32_fp8_e32 v[44:45], v188
	v_cvt_pk_f32_fp8_sdwa v[46:47], v188 src0_sel:WORD_1
	v_cvt_pk_f32_fp8_e32 v[48:49], v189
	v_cvt_pk_f32_fp8_sdwa v[50:51], v189 src0_sel:WORD_1
	v_cvt_pk_f32_fp8_e32 v[52:53], v190
	v_cvt_pk_f32_fp8_sdwa v[54:55], v190 src0_sel:WORD_1
	v_cvt_pk_f32_fp8_e32 v[56:57], v191
	v_cvt_pk_f32_fp8_sdwa v[58:59], v191 src0_sel:WORD_1
	v_cvt_pk_f32_fp8_e32 v[66:67], v192
	v_cvt_pk_f32_fp8_sdwa v[68:69], v192 src0_sel:WORD_1
	v_cvt_pk_f32_fp8_e32 v[70:71], v193
	v_cvt_pk_f32_fp8_sdwa v[72:73], v193 src0_sel:WORD_1
	v_cvt_pk_f32_fp8_e32 v[74:75], v194
	v_cvt_pk_f32_fp8_sdwa v[76:77], v194 src0_sel:WORD_1
	v_cvt_pk_f32_fp8_e32 v[78:79], v195
	v_cvt_pk_f32_fp8_sdwa v[80:81], v195 src0_sel:WORD_1
	v_pk_mul_f32 v[82:83], v[44:45], v[28:29]
	v_pk_mul_f32 v[86:87], v[66:67], v[28:29]
	v_pk_mul_f32 v[84:85], v[46:47], v[30:31]
	v_pk_mul_f32 v[88:89], v[68:69], v[30:31]
	v_pk_fma_f32 v[82:83], v[48:49], v[32:33], v[82:83]
	v_pk_fma_f32 v[86:87], v[70:71], v[32:33], v[86:87]
	v_pk_fma_f32 v[84:85], v[50:51], v[34:35], v[84:85]
	v_pk_fma_f32 v[88:89], v[72:73], v[34:35], v[88:89]
	v_pk_fma_f32 v[82:83], v[52:53], v[36:37], v[82:83]
	v_pk_fma_f32 v[86:87], v[74:75], v[36:37], v[86:87]
	v_pk_fma_f32 v[84:85], v[54:55], v[38:39], v[84:85]
	v_pk_fma_f32 v[88:89], v[76:77], v[38:39], v[88:89]
	v_pk_fma_f32 v[82:83], v[56:57], v[40:41], v[82:83]
	v_pk_fma_f32 v[86:87], v[78:79], v[40:41], v[86:87]
	v_pk_fma_f32 v[84:85], v[58:59], v[42:43], v[84:85]
	v_pk_fma_f32 v[88:89], v[80:81], v[42:43], v[88:89]
	v_pk_add_f32 v[82:83], v[82:83], v[84:85]
	v_pk_add_f32 v[86:87], v[86:87], v[88:89]
	v_lshl_add_u32 v11, v110, 10, v8
	v_add_f32_e32 v90, v82, v83
	v_add_f32_e32 v94, v86, v87
	global_load_dwordx4 v[188:191], v11, s[6:7]
	v_lshl_add_u32 v65, v111, 10, v8
	v_add_f32_dpp v91, v90, v90 quad_perm:[1,0,3,2] row_mask:0xf bank_mask:0xf
	v_add_f32_dpp v95, v94, v94 quad_perm:[1,0,3,2] row_mask:0xf bank_mask:0xf
	global_load_dwordx4 v[192:195], v65, s[6:7]
	v_add_f32_dpp v92, v91, v91 quad_perm:[2,3,0,1] row_mask:0xf bank_mask:0xf
	v_add_f32_dpp v96, v95, v95 quad_perm:[2,3,0,1] row_mask:0xf bank_mask:0xf
	s_nop 0
	v_add_f32_dpp v93, v92, v92 row_half_mirror row_mask:0xf bank_mask:0xf
	v_add_f32_dpp v97, v96, v96 row_half_mirror row_mask:0xf bank_mask:0xf
	v_fmac_f32_e32 v99, v93, v14
	v_fmac_f32_e32 v99, v97, v15
	s_waitcnt vmcnt(17)
; DI void phase_peer_down(const Params& p) {
;     ...
;       for (int bi = 0; bi < 8; ++bi) {
;         u32x4 dr[8];
; #pragma unroll
;         for (int k = 0; k < 8; ++k) {
;           const int er = __builtin_amdgcn_readlane(ev, bi * 8 + k);
;           dr[k] = *reinterpret_cast<const u32x4*>(exd + (size_t)er * 1024 + lane * 16);
;         }
;         const int pmine = bi * 8 + (lane & 7);
;         const int emine = __shfl(ev, pmine);
;         const float gsel = __shfl(gv, pmine);
;         const float sd = esc[emine];
;         const float su = esc[16384 + emine];
;         float part[8];
; #pragma unroll
;         for (int k = 0; k < 8; ++k) {
;           float a0 = 0.f, a1 = 0.f;
; #pragma unroll
;           for (int w = 0; w < 4; ++w) {
;             f2_t lo = __builtin_amdgcn_cvt_pk_f32_fp8((int)dr[k][w], false);
;             f2_t hi = __builtin_amdgcn_cvt_pk_f32_fp8((int)dr[k][w], true);
;             a0 = fmaf(lo[0], x[4 * w], a0); a1 = fmaf(lo[1], x[4 * w + 1], a1);
;             a0 = fmaf(hi[0], x[4 * w + 2], a0); a1 = fmaf(hi[1], x[4 * w + 3], a1);
;           }
;           part[k] = a0 + a1;
;         }
;         const float r1 = reduce8(part, lane) * sd;
;         const bool mine = (lane >> 3) == bi;
;         racc = mine ? r1 : racc; gacc = mine ? gsel * su : gacc;
;       }
	v_cvt_pk_f32_fp8_e32 v[44:45], v196
	v_cvt_pk_f32_fp8_sdwa v[46:47], v196 src0_sel:WORD_1
	v_cvt_pk_f32_fp8_e32 v[48:49], v197
	v_cvt_pk_f32_fp8_sdwa v[50:51], v197 src0_sel:WORD_1
	v_cvt_pk_f32_fp8_e32 v[52:53], v198
	v_cvt_pk_f32_fp8_sdwa v[54:55], v198 src0_sel:WORD_1
	v_cvt_pk_f32_fp8_e32 v[56:57], v199
	v_cvt_pk_f32_fp8_sdwa v[58:59], v199 src0_sel:WORD_1
	v_cvt_pk_f32_fp8_e32 v[66:67], v200
	v_cvt_pk_f32_fp8_sdwa v[68:69], v200 src0_sel:WORD_1
	v_cvt_pk_f32_fp8_e32 v[70:71], v201
	v_cvt_pk_f32_fp8_sdwa v[72:73], v201 src0_sel:WORD_1
	v_cvt_pk_f32_fp8_e32 v[74:75], v202
	v_cvt_pk_f32_fp8_sdwa v[76:77], v202 src0_sel:WORD_1
	v_cvt_pk_f32_fp8_e32 v[78:79], v203
	v_cvt_pk_f32_fp8_sdwa v[80:81], v203 src0_sel:WORD_1
	v_pk_mul_f32 v[82:83], v[44:45], v[28:29]
	v_pk_mul_f32 v[86:87], v[66:67], v[28:29]
	v_pk_mul_f32 v[84:85], v[46:47], v[30:31]
	v_pk_mul_f32 v[88:89], v[68:69], v[30:31]
	v_pk_fma_f32 v[82:83], v[48:49], v[32:33], v[82:83]
	v_pk_fma_f32 v[86:87], v[70:71], v[32:33], v[86:87]
	v_pk_fma_f32 v[84:85], v[50:51], v[34:35], v[84:85]
	v_pk_fma_f32 v[88:89], v[72:73], v[34:35], v[88:89]
	v_pk_fma_f32 v[82:83], v[52:53], v[36:37], v[82:83]
	v_pk_fma_f32 v[86:87], v[74:75], v[36:37], v[86:87]
	v_pk_fma_f32 v[84:85], v[54:55], v[38:39], v[84:85]
	v_pk_fma_f32 v[88:89], v[76:77], v[38:39], v[88:89]
	v_pk_fma_f32 v[82:83], v[56:57], v[40:41], v[82:83]
	v_pk_fma_f32 v[86:87], v[78:79], v[40:41], v[86:87]
	v_pk_fma_f32 v[84:85], v[58:59], v[42:43], v[84:85]
	v_pk_fma_f32 v[88:89], v[80:81], v[42:43], v[88:89]
	v_pk_add_f32 v[82:83], v[82:83], v[84:85]
	v_pk_add_f32 v[86:87], v[86:87], v[88:89]
	v_lshl_add_u32 v11, v112, 10, v8
	v_add_f32_e32 v90, v82, v83
	v_add_f32_e32 v94, v86, v87
	global_load_dwordx4 v[196:199], v11, s[6:7]
	v_lshl_add_u32 v65, v113, 10, v8
	v_add_f32_dpp v91, v90, v90 quad_perm:[1,0,3,2] row_mask:0xf bank_mask:0xf
	v_add_f32_dpp v95, v94, v94 quad_perm:[1,0,3,2] row_mask:0xf bank_mask:0xf
	global_load_dwordx4 v[200:203], v65, s[6:7]
	v_add_f32_dpp v92, v91, v91 quad_perm:[2,3,0,1] row_mask:0xf bank_mask:0xf
	v_add_f32_dpp v96, v95, v95 quad_perm:[2,3,0,1] row_mask:0xf bank_mask:0xf
	s_nop 0
	v_add_f32_dpp v93, v92, v92 row_half_mirror row_mask:0xf bank_mask:0xf
	v_add_f32_dpp v97, v96, v96 row_half_mirror row_mask:0xf bank_mask:0xf
	v_fmac_f32_e32 v99, v93, v16
	v_fmac_f32_e32 v99, v97, v17
	s_waitcnt vmcnt(17)
	v_cvt_pk_f32_fp8_e32 v[44:45], v204
	v_cvt_pk_f32_fp8_sdwa v[46:47], v204 src0_sel:WORD_1
	v_cvt_pk_f32_fp8_e32 v[48:49], v205
	v_cvt_pk_f32_fp8_sdwa v[50:51], v205 src0_sel:WORD_1
	v_cvt_pk_f32_fp8_e32 v[52:53], v206
	v_cvt_pk_f32_fp8_sdwa v[54:55], v206 src0_sel:WORD_1
	v_cvt_pk_f32_fp8_e32 v[56:57], v207
	v_cvt_pk_f32_fp8_sdwa v[58:59], v207 src0_sel:WORD_1
	v_cvt_pk_f32_fp8_e32 v[66:67], v208
	v_cvt_pk_f32_fp8_sdwa v[68:69], v208 src0_sel:WORD_1
	v_cvt_pk_f32_fp8_e32 v[70:71], v209
	v_cvt_pk_f32_fp8_sdwa v[72:73], v209 src0_sel:WORD_1
	v_cvt_pk_f32_fp8_e32 v[74:75], v210
	v_cvt_pk_f32_fp8_sdwa v[76:77], v210 src0_sel:WORD_1
	v_cvt_pk_f32_fp8_e32 v[78:79], v211
	v_cvt_pk_f32_fp8_sdwa v[80:81], v211 src0_sel:WORD_1
	v_pk_mul_f32 v[82:83], v[44:45], v[28:29]
	v_pk_mul_f32 v[86:87], v[66:67], v[28:29]
	v_pk_mul_f32 v[84:85], v[46:47], v[30:31]
	v_pk_mul_f32 v[88:89], v[68:69], v[30:31]
	v_pk_fma_f32 v[82:83], v[48:49], v[32:33], v[82:83]
	v_pk_fma_f32 v[86:87], v[70:71], v[32:33], v[86:87]
	v_pk_fma_f32 v[84:85], v[50:51], v[34:35], v[84:85]
	v_pk_fma_f32 v[88:89], v[72:73], v[34:35], v[88:89]
	v_pk_fma_f32 v[82:83], v[52:53], v[36:37], v[82:83]
	v_pk_fma_f32 v[86:87], v[74:75], v[36:37], v[86:87]
	v_pk_fma_f32 v[84:85], v[54:55], v[38:39], v[84:85]
	v_pk_fma_f32 v[88:89], v[76:77], v[38:39], v[88:89]
	v_pk_fma_f32 v[82:83], v[56:57], v[40:41], v[82:83]
	v_pk_fma_f32 v[86:87], v[78:79], v[40:41], v[86:87]
	v_pk_fma_f32 v[84:85], v[58:59], v[42:43], v[84:85]
	v_pk_fma_f32 v[88:89], v[80:81], v[42:43], v[88:89]
	v_pk_add_f32 v[82:83], v[82:83], v[84:85]
	v_pk_add_f32 v[86:87], v[86:87], v[88:89]
	v_lshl_add_u32 v11, v114, 10, v8
	v_add_f32_e32 v90, v82, v83
	v_add_f32_e32 v94, v86, v87
	global_load_dwordx4 v[204:207], v11, s[6:7]
	v_lshl_add_u32 v65, v115, 10, v8
	v_add_f32_dpp v91, v90, v90 quad_perm:[1,0,3,2] row_mask:0xf bank_mask:0xf
	v_add_f32_dpp v95, v94, v94 quad_perm:[1,0,3,2] row_mask:0xf bank_mask:0xf
	global_load_dwordx4 v[208:211], v65, s[6:7]
	v_add_f32_dpp v92, v91, v91 quad_perm:[2,3,0,1] row_mask:0xf bank_mask:0xf
	v_add_f32_dpp v96, v95, v95 quad_perm:[2,3,0,1] row_mask:0xf bank_mask:0xf
	s_nop 0
	v_add_f32_dpp v93, v92, v92 row_half_mirror row_mask:0xf bank_mask:0xf
	v_add_f32_dpp v97, v96, v96 row_half_mirror row_mask:0xf bank_mask:0xf
	v_fmac_f32_e32 v99, v93, v18
	v_fmac_f32_e32 v99, v97, v19
	ds_write_b64 v10, v[98:99]
	s_add_i32 s18, s18, 1
	s_add_i32 s20, s18, 1
	s_min_i32 s20, s20, 0x7f
	s_lshr_b32 s21, s20, 4
	s_and_b32 s22, s20, 15
	s_add_i32 s23, s18, 2
	s_min_i32 s23, s23, 0x7f
	s_and_b32 s24, s23, 15
	s_and_b32 s26, s18, 15
	s_lshl_b32 s22, s22, 11
	s_lshl_b32 s24, s24, 11
	s_lshl_b32 s27, s21, 8
	s_lshl_b32 s28, s21, 7
	s_lshl_b32 s29, s26, 9
	v_add_u32_e32 v5, s22, v64
	v_add_u32_e32 v6, s24, v64
	v_add_u32_e32 v10, s29, v4
	v_lshl_add_u32 v7, v5, 11, v3
	v_add_u32_e32 v7, s27, v7
	v_add_u32_e32 v8, s28, v2
	v_lshl_add_u32 v9, v6, 9, v212
	ds_read_b64 v[98:99], v10
	s_waitcnt vmcnt(16)
; DI void phase_peer_down(const Params& p) {
;     ...
;       for (int bi = 0; bi < 8; ++bi) {
;         u32x4 dr[8];
; #pragma unroll
;         for (int k = 0; k < 8; ++k) {
;           const int er = __builtin_amdgcn_readlane(ev, bi * 8 + k);
;           dr[k] = *reinterpret_cast<const u32x4*>(exd + (size_t)er * 1024 + lane * 16);
;         }
;         const int pmine = bi * 8 + (lane & 7);
;         const int emine = __shfl(ev, pmine);
;         const float gsel = __shfl(gv, pmine);
;         const float sd = esc[emine];
;         const float su = esc[16384 + emine];
;         float part[8];
; #pragma unroll
;         for (int k = 0; k < 8; ++k) {
;           float a0 = 0.f, a1 = 0.f;
; #pragma unroll
;           for (int w = 0; w < 4; ++w) {
;             f2_t lo = __builtin_amdgcn_cvt_pk_f32_fp8((int)dr[k][w], false);
;             f2_t hi = __builtin_amdgcn_cvt_pk_f32_fp8((int)dr[k][w], true);
;             a0 = fmaf(lo[0], x[4 * w], a0); a1 = fmaf(lo[1], x[4 * w + 1], a1);
;             a0 = fmaf(hi[0], x[4 * w + 2], a0); a1 = fmaf(hi[1], x[4 * w + 3], a1);
;           }
;           part[k] = a0 + a1;
;         }
;         const float r1 = reduce8(part, lane) * sd;
;         const bool mine = (lane >> 3) == bi;
;         racc = mine ? r1 : racc; gacc = mine ? gsel * su : gacc;
;       }
	v_lshlrev_b32_e32 v28, 16, v20
	v_and_b32_e32 v29, 0xffff0000, v20
	v_lshlrev_b32_e32 v30, 16, v21
	v_and_b32_e32 v31, 0xffff0000, v21
	v_lshlrev_b32_e32 v32, 16, v22
	v_and_b32_e32 v33, 0xffff0000, v22
	v_lshlrev_b32_e32 v34, 16, v23
	v_and_b32_e32 v35, 0xffff0000, v23
	v_lshlrev_b32_e32 v36, 16, v24
	v_and_b32_e32 v37, 0xffff0000, v24
	v_lshlrev_b32_e32 v38, 16, v25
	v_and_b32_e32 v39, 0xffff0000, v25
	v_lshlrev_b32_e32 v40, 16, v26
	v_and_b32_e32 v41, 0xffff0000, v26
	v_lshlrev_b32_e32 v42, 16, v27
	v_and_b32_e32 v43, 0xffff0000, v27
	global_load_dwordx4 v[20:23], v7, s[8:9]
	global_load_dwordx4 v[24:27], v7, s[8:9] offset:16
	ds_write_b64 v213, v[216:217]
	ds_read_b128 v[100:103], v214 offset:0
	ds_read_b128 v[104:107], v214 offset:16
	ds_read_b128 v[108:111], v214 offset:32
	ds_read_b128 v[112:115], v214 offset:48
	global_load_dwordx2 v[216:217], v9, s[4:5]
	s_waitcnt lgkmcnt(0)
	s_waitcnt vmcnt(17)
	v_cvt_pk_f32_fp8_e32 v[44:45], v116
	v_cvt_pk_f32_fp8_sdwa v[46:47], v116 src0_sel:WORD_1
	v_cvt_pk_f32_fp8_e32 v[48:49], v117
	v_cvt_pk_f32_fp8_sdwa v[50:51], v117 src0_sel:WORD_1
	v_cvt_pk_f32_fp8_e32 v[52:53], v118
	v_cvt_pk_f32_fp8_sdwa v[54:55], v118 src0_sel:WORD_1
	v_cvt_pk_f32_fp8_e32 v[56:57], v119
	v_cvt_pk_f32_fp8_sdwa v[58:59], v119 src0_sel:WORD_1
	v_cvt_pk_f32_fp8_e32 v[66:67], v120
	v_cvt_pk_f32_fp8_sdwa v[68:69], v120 src0_sel:WORD_1
	v_cvt_pk_f32_fp8_e32 v[70:71], v121
	v_cvt_pk_f32_fp8_sdwa v[72:73], v121 src0_sel:WORD_1
	v_cvt_pk_f32_fp8_e32 v[74:75], v122
	v_cvt_pk_f32_fp8_sdwa v[76:77], v122 src0_sel:WORD_1
	v_cvt_pk_f32_fp8_e32 v[78:79], v123
	v_cvt_pk_f32_fp8_sdwa v[80:81], v123 src0_sel:WORD_1
	v_pk_mul_f32 v[82:83], v[44:45], v[28:29]
	v_pk_mul_f32 v[86:87], v[66:67], v[28:29]
	v_pk_mul_f32 v[84:85], v[46:47], v[30:31]
	v_pk_mul_f32 v[88:89], v[68:69], v[30:31]
	v_pk_fma_f32 v[82:83], v[48:49], v[32:33], v[82:83]
	v_pk_fma_f32 v[86:87], v[70:71], v[32:33], v[86:87]
	v_pk_fma_f32 v[84:85], v[50:51], v[34:35], v[84:85]
	v_pk_fma_f32 v[88:89], v[72:73], v[34:35], v[88:89]
	v_pk_fma_f32 v[82:83], v[52:53], v[36:37], v[82:83]
	v_pk_fma_f32 v[86:87], v[74:75], v[36:37], v[86:87]
	v_pk_fma_f32 v[84:85], v[54:55], v[38:39], v[84:85]
	v_pk_fma_f32 v[88:89], v[76:77], v[38:39], v[88:89]
	v_pk_fma_f32 v[82:83], v[56:57], v[40:41], v[82:83]
	v_pk_fma_f32 v[86:87], v[78:79], v[40:41], v[86:87]
	v_pk_fma_f32 v[84:85], v[58:59], v[42:43], v[84:85]
	v_pk_fma_f32 v[88:89], v[80:81], v[42:43], v[88:89]
	v_pk_add_f32 v[82:83], v[82:83], v[84:85]
	v_pk_add_f32 v[86:87], v[86:87], v[88:89]
	v_lshl_add_u32 v11, v100, 10, v8
	v_add_f32_e32 v90, v82, v83
	v_add_f32_e32 v94, v86, v87
	global_load_dwordx4 v[116:119], v11, s[6:7]
	v_lshl_add_u32 v65, v101, 10, v8
	v_add_f32_dpp v91, v90, v90 quad_perm:[1,0,3,2] row_mask:0xf bank_mask:0xf
	v_add_f32_dpp v95, v94, v94 quad_perm:[1,0,3,2] row_mask:0xf bank_mask:0xf
	global_load_dwordx4 v[120:123], v65, s[6:7]
	v_add_f32_dpp v92, v91, v91 quad_perm:[2,3,0,1] row_mask:0xf bank_mask:0xf
	v_add_f32_dpp v96, v95, v95 quad_perm:[2,3,0,1] row_mask:0xf bank_mask:0xf
	s_nop 0
	v_add_f32_dpp v93, v92, v92 row_half_mirror row_mask:0xf bank_mask:0xf
	v_add_f32_dpp v97, v96, v96 row_half_mirror row_mask:0xf bank_mask:0xf
	v_fmac_f32_e32 v98, v93, v12
	v_fmac_f32_e32 v98, v97, v13
	s_waitcnt vmcnt(17)
	v_cvt_pk_f32_fp8_e32 v[44:45], v124
	v_cvt_pk_f32_fp8_sdwa v[46:47], v124 src0_sel:WORD_1
	v_cvt_pk_f32_fp8_e32 v[48:49], v125
	v_cvt_pk_f32_fp8_sdwa v[50:51], v125 src0_sel:WORD_1
	v_cvt_pk_f32_fp8_e32 v[52:53], v126
	v_cvt_pk_f32_fp8_sdwa v[54:55], v126 src0_sel:WORD_1
	v_cvt_pk_f32_fp8_e32 v[56:57], v127
	v_cvt_pk_f32_fp8_sdwa v[58:59], v127 src0_sel:WORD_1
	v_cvt_pk_f32_fp8_e32 v[66:67], v128
	v_cvt_pk_f32_fp8_sdwa v[68:69], v128 src0_sel:WORD_1
	v_cvt_pk_f32_fp8_e32 v[70:71], v129
	v_cvt_pk_f32_fp8_sdwa v[72:73], v129 src0_sel:WORD_1
	v_cvt_pk_f32_fp8_e32 v[74:75], v130
	v_cvt_pk_f32_fp8_sdwa v[76:77], v130 src0_sel:WORD_1
	v_cvt_pk_f32_fp8_e32 v[78:79], v131
	v_cvt_pk_f32_fp8_sdwa v[80:81], v131 src0_sel:WORD_1
	v_pk_mul_f32 v[82:83], v[44:45], v[28:29]
	v_pk_mul_f32 v[86:87], v[66:67], v[28:29]
	v_pk_mul_f32 v[84:85], v[46:47], v[30:31]
	v_pk_mul_f32 v[88:89], v[68:69], v[30:31]
	v_pk_fma_f32 v[82:83], v[48:49], v[32:33], v[82:83]
	v_pk_fma_f32 v[86:87], v[70:71], v[32:33], v[86:87]
	v_pk_fma_f32 v[84:85], v[50:51], v[34:35], v[84:85]
	v_pk_fma_f32 v[88:89], v[72:73], v[34:35], v[88:89]
	v_pk_fma_f32 v[82:83], v[52:53], v[36:37], v[82:83]
	v_pk_fma_f32 v[86:87], v[74:75], v[36:37], v[86:87]
	v_pk_fma_f32 v[84:85], v[54:55], v[38:39], v[84:85]
	v_pk_fma_f32 v[88:89], v[76:77], v[38:39], v[88:89]
	v_pk_fma_f32 v[82:83], v[56:57], v[40:41], v[82:83]
	v_pk_fma_f32 v[86:87], v[78:79], v[40:41], v[86:87]
	v_pk_fma_f32 v[84:85], v[58:59], v[42:43], v[84:85]
	v_pk_fma_f32 v[88:89], v[80:81], v[42:43], v[88:89]
	v_pk_add_f32 v[82:83], v[82:83], v[84:85]
	v_pk_add_f32 v[86:87], v[86:87], v[88:89]
	v_lshl_add_u32 v11, v102, 10, v8
	v_add_f32_e32 v90, v82, v83
	v_add_f32_e32 v94, v86, v87
	global_load_dwordx4 v[124:127], v11, s[6:7]
	v_lshl_add_u32 v65, v103, 10, v8
	v_add_f32_dpp v91, v90, v90 quad_perm:[1,0,3,2] row_mask:0xf bank_mask:0xf
	v_add_f32_dpp v95, v94, v94 quad_perm:[1,0,3,2] row_mask:0xf bank_mask:0xf
	global_load_dwordx4 v[128:131], v65, s[6:7]
	v_add_f32_dpp v92, v91, v91 quad_perm:[2,3,0,1] row_mask:0xf bank_mask:0xf
	v_add_f32_dpp v96, v95, v95 quad_perm:[2,3,0,1] row_mask:0xf bank_mask:0xf
	s_nop 0
	v_add_f32_dpp v93, v92, v92 row_half_mirror row_mask:0xf bank_mask:0xf
	v_add_f32_dpp v97, v96, v96 row_half_mirror row_mask:0xf bank_mask:0xf
	v_fmac_f32_e32 v98, v93, v14
	v_fmac_f32_e32 v98, v97, v15
	s_waitcnt vmcnt(17)
; DI void phase_peer_down(const Params& p) {
;     ...
;       for (int bi = 0; bi < 8; ++bi) {
;         u32x4 dr[8];
; #pragma unroll
;         for (int k = 0; k < 8; ++k) {
;           const int er = __builtin_amdgcn_readlane(ev, bi * 8 + k);
;           dr[k] = *reinterpret_cast<const u32x4*>(exd + (size_t)er * 1024 + lane * 16);
;         }
;         const int pmine = bi * 8 + (lane & 7);
;         const int emine = __shfl(ev, pmine);
;         const float gsel = __shfl(gv, pmine);
;         const float sd = esc[emine];
;         const float su = esc[16384 + emine];
;         float part[8];
; #pragma unroll
;         for (int k = 0; k < 8; ++k) {
;           float a0 = 0.f, a1 = 0.f;
; #pragma unroll
;           for (int w = 0; w < 4; ++w) {
;             f2_t lo = __builtin_amdgcn_cvt_pk_f32_fp8((int)dr[k][w], false);
;             f2_t hi = __builtin_amdgcn_cvt_pk_f32_fp8((int)dr[k][w], true);
;             a0 = fmaf(lo[0], x[4 * w], a0); a1 = fmaf(lo[1], x[4 * w + 1], a1);
;             a0 = fmaf(hi[0], x[4 * w + 2], a0); a1 = fmaf(hi[1], x[4 * w + 3], a1);
;           }
;           part[k] = a0 + a1;
;         }
;         const float r1 = reduce8(part, lane) * sd;
;         const bool mine = (lane >> 3) == bi;
;         racc = mine ? r1 : racc; gacc = mine ? gsel * su : gacc;
;       }
	v_cvt_pk_f32_fp8_e32 v[44:45], v132
	v_cvt_pk_f32_fp8_sdwa v[46:47], v132 src0_sel:WORD_1
	v_cvt_pk_f32_fp8_e32 v[48:49], v133
	v_cvt_pk_f32_fp8_sdwa v[50:51], v133 src0_sel:WORD_1
	v_cvt_pk_f32_fp8_e32 v[52:53], v134
	v_cvt_pk_f32_fp8_sdwa v[54:55], v134 src0_sel:WORD_1
	v_cvt_pk_f32_fp8_e32 v[56:57], v135
	v_cvt_pk_f32_fp8_sdwa v[58:59], v135 src0_sel:WORD_1
	v_cvt_pk_f32_fp8_e32 v[66:67], v136
	v_cvt_pk_f32_fp8_sdwa v[68:69], v136 src0_sel:WORD_1
	v_cvt_pk_f32_fp8_e32 v[70:71], v137
	v_cvt_pk_f32_fp8_sdwa v[72:73], v137 src0_sel:WORD_1
	v_cvt_pk_f32_fp8_e32 v[74:75], v138
	v_cvt_pk_f32_fp8_sdwa v[76:77], v138 src0_sel:WORD_1
	v_cvt_pk_f32_fp8_e32 v[78:79], v139
	v_cvt_pk_f32_fp8_sdwa v[80:81], v139 src0_sel:WORD_1
	v_pk_mul_f32 v[82:83], v[44:45], v[28:29]
	v_pk_mul_f32 v[86:87], v[66:67], v[28:29]
	v_pk_mul_f32 v[84:85], v[46:47], v[30:31]
	v_pk_mul_f32 v[88:89], v[68:69], v[30:31]
	v_pk_fma_f32 v[82:83], v[48:49], v[32:33], v[82:83]
	v_pk_fma_f32 v[86:87], v[70:71], v[32:33], v[86:87]
	v_pk_fma_f32 v[84:85], v[50:51], v[34:35], v[84:85]
	v_pk_fma_f32 v[88:89], v[72:73], v[34:35], v[88:89]
	v_pk_fma_f32 v[82:83], v[52:53], v[36:37], v[82:83]
	v_pk_fma_f32 v[86:87], v[74:75], v[36:37], v[86:87]
	v_pk_fma_f32 v[84:85], v[54:55], v[38:39], v[84:85]
	v_pk_fma_f32 v[88:89], v[76:77], v[38:39], v[88:89]
	v_pk_fma_f32 v[82:83], v[56:57], v[40:41], v[82:83]
	v_pk_fma_f32 v[86:87], v[78:79], v[40:41], v[86:87]
	v_pk_fma_f32 v[84:85], v[58:59], v[42:43], v[84:85]
	v_pk_fma_f32 v[88:89], v[80:81], v[42:43], v[88:89]
	v_pk_add_f32 v[82:83], v[82:83], v[84:85]
	v_pk_add_f32 v[86:87], v[86:87], v[88:89]
	v_lshl_add_u32 v11, v104, 10, v8
	v_add_f32_e32 v90, v82, v83
	v_add_f32_e32 v94, v86, v87
	global_load_dwordx4 v[132:135], v11, s[6:7]
	v_lshl_add_u32 v65, v105, 10, v8
	v_add_f32_dpp v91, v90, v90 quad_perm:[1,0,3,2] row_mask:0xf bank_mask:0xf
	v_add_f32_dpp v95, v94, v94 quad_perm:[1,0,3,2] row_mask:0xf bank_mask:0xf
	global_load_dwordx4 v[136:139], v65, s[6:7]
	v_add_f32_dpp v92, v91, v91 quad_perm:[2,3,0,1] row_mask:0xf bank_mask:0xf
	v_add_f32_dpp v96, v95, v95 quad_perm:[2,3,0,1] row_mask:0xf bank_mask:0xf
	s_nop 0
	v_add_f32_dpp v93, v92, v92 row_half_mirror row_mask:0xf bank_mask:0xf
	v_add_f32_dpp v97, v96, v96 row_half_mirror row_mask:0xf bank_mask:0xf
	v_fmac_f32_e32 v98, v93, v16
	v_fmac_f32_e32 v98, v97, v17
	s_waitcnt vmcnt(17)
	v_cvt_pk_f32_fp8_e32 v[44:45], v140
	v_cvt_pk_f32_fp8_sdwa v[46:47], v140 src0_sel:WORD_1
	v_cvt_pk_f32_fp8_e32 v[48:49], v141
	v_cvt_pk_f32_fp8_sdwa v[50:51], v141 src0_sel:WORD_1
	v_cvt_pk_f32_fp8_e32 v[52:53], v142
	v_cvt_pk_f32_fp8_sdwa v[54:55], v142 src0_sel:WORD_1
	v_cvt_pk_f32_fp8_e32 v[56:57], v143
	v_cvt_pk_f32_fp8_sdwa v[58:59], v143 src0_sel:WORD_1
	v_cvt_pk_f32_fp8_e32 v[66:67], v144
	v_cvt_pk_f32_fp8_sdwa v[68:69], v144 src0_sel:WORD_1
	v_cvt_pk_f32_fp8_e32 v[70:71], v145
	v_cvt_pk_f32_fp8_sdwa v[72:73], v145 src0_sel:WORD_1
	v_cvt_pk_f32_fp8_e32 v[74:75], v146
	v_cvt_pk_f32_fp8_sdwa v[76:77], v146 src0_sel:WORD_1
	v_cvt_pk_f32_fp8_e32 v[78:79], v147
	v_cvt_pk_f32_fp8_sdwa v[80:81], v147 src0_sel:WORD_1
	v_pk_mul_f32 v[82:83], v[44:45], v[28:29]
	v_pk_mul_f32 v[86:87], v[66:67], v[28:29]
	v_pk_mul_f32 v[84:85], v[46:47], v[30:31]
	v_pk_mul_f32 v[88:89], v[68:69], v[30:31]
	v_pk_fma_f32 v[82:83], v[48:49], v[32:33], v[82:83]
	v_pk_fma_f32 v[86:87], v[70:71], v[32:33], v[86:87]
	v_pk_fma_f32 v[84:85], v[50:51], v[34:35], v[84:85]
	v_pk_fma_f32 v[88:89], v[72:73], v[34:35], v[88:89]
	v_pk_fma_f32 v[82:83], v[52:53], v[36:37], v[82:83]
	v_pk_fma_f32 v[86:87], v[74:75], v[36:37], v[86:87]
	v_pk_fma_f32 v[84:85], v[54:55], v[38:39], v[84:85]
	v_pk_fma_f32 v[88:89], v[76:77], v[38:39], v[88:89]
	v_pk_fma_f32 v[82:83], v[56:57], v[40:41], v[82:83]
	v_pk_fma_f32 v[86:87], v[78:79], v[40:41], v[86:87]
	v_pk_fma_f32 v[84:85], v[58:59], v[42:43], v[84:85]
	v_pk_fma_f32 v[88:89], v[80:81], v[42:43], v[88:89]
	v_pk_add_f32 v[82:83], v[82:83], v[84:85]
	v_pk_add_f32 v[86:87], v[86:87], v[88:89]
	v_lshl_add_u32 v11, v106, 10, v8
	v_add_f32_e32 v90, v82, v83
	v_add_f32_e32 v94, v86, v87
	global_load_dwordx4 v[140:143], v11, s[6:7]
	v_lshl_add_u32 v65, v107, 10, v8
	v_add_f32_dpp v91, v90, v90 quad_perm:[1,0,3,2] row_mask:0xf bank_mask:0xf
	v_add_f32_dpp v95, v94, v94 quad_perm:[1,0,3,2] row_mask:0xf bank_mask:0xf
	global_load_dwordx4 v[144:147], v65, s[6:7]
	v_add_f32_dpp v92, v91, v91 quad_perm:[2,3,0,1] row_mask:0xf bank_mask:0xf
	v_add_f32_dpp v96, v95, v95 quad_perm:[2,3,0,1] row_mask:0xf bank_mask:0xf
	s_nop 0
	v_add_f32_dpp v93, v92, v92 row_half_mirror row_mask:0xf bank_mask:0xf
	v_add_f32_dpp v97, v96, v96 row_half_mirror row_mask:0xf bank_mask:0xf
	v_fmac_f32_e32 v98, v93, v18
	v_fmac_f32_e32 v98, v97, v19
	s_waitcnt vmcnt(17)
; DI void phase_peer_down(const Params& p) {
;     ...
;       for (int bi = 0; bi < 8; ++bi) {
;         u32x4 dr[8];
; #pragma unroll
;         for (int k = 0; k < 8; ++k) {
;           const int er = __builtin_amdgcn_readlane(ev, bi * 8 + k);
;           dr[k] = *reinterpret_cast<const u32x4*>(exd + (size_t)er * 1024 + lane * 16);
;         }
;         const int pmine = bi * 8 + (lane & 7);
;         const int emine = __shfl(ev, pmine);
;         const float gsel = __shfl(gv, pmine);
;         const float sd = esc[emine];
;         const float su = esc[16384 + emine];
;         float part[8];
; #pragma unroll
;         for (int k = 0; k < 8; ++k) {
;           float a0 = 0.f, a1 = 0.f;
; #pragma unroll
;           for (int w = 0; w < 4; ++w) {
;             f2_t lo = __builtin_amdgcn_cvt_pk_f32_fp8((int)dr[k][w], false);
;             f2_t hi = __builtin_amdgcn_cvt_pk_f32_fp8((int)dr[k][w], true);
;             a0 = fmaf(lo[0], x[4 * w], a0); a1 = fmaf(lo[1], x[4 * w + 1], a1);
;             a0 = fmaf(hi[0], x[4 * w + 2], a0); a1 = fmaf(hi[1], x[4 * w + 3], a1);
;           }
;           part[k] = a0 + a1;
;         }
;         const float r1 = reduce8(part, lane) * sd;
;         const bool mine = (lane >> 3) == bi;
;         racc = mine ? r1 : racc; gacc = mine ? gsel * su : gacc;
;       }
	v_cvt_pk_f32_fp8_e32 v[44:45], v180
	v_cvt_pk_f32_fp8_sdwa v[46:47], v180 src0_sel:WORD_1
	v_cvt_pk_f32_fp8_e32 v[48:49], v181
	v_cvt_pk_f32_fp8_sdwa v[50:51], v181 src0_sel:WORD_1
	v_cvt_pk_f32_fp8_e32 v[52:53], v182
	v_cvt_pk_f32_fp8_sdwa v[54:55], v182 src0_sel:WORD_1
	v_cvt_pk_f32_fp8_e32 v[56:57], v183
	v_cvt_pk_f32_fp8_sdwa v[58:59], v183 src0_sel:WORD_1
	v_cvt_pk_f32_fp8_e32 v[66:67], v184
	v_cvt_pk_f32_fp8_sdwa v[68:69], v184 src0_sel:WORD_1
	v_cvt_pk_f32_fp8_e32 v[70:71], v185
	v_cvt_pk_f32_fp8_sdwa v[72:73], v185 src0_sel:WORD_1
	v_cvt_pk_f32_fp8_e32 v[74:75], v186
	v_cvt_pk_f32_fp8_sdwa v[76:77], v186 src0_sel:WORD_1
	v_cvt_pk_f32_fp8_e32 v[78:79], v187
	v_cvt_pk_f32_fp8_sdwa v[80:81], v187 src0_sel:WORD_1
	v_pk_mul_f32 v[82:83], v[44:45], v[28:29]
	v_pk_mul_f32 v[86:87], v[66:67], v[28:29]
	v_pk_mul_f32 v[84:85], v[46:47], v[30:31]
	v_pk_mul_f32 v[88:89], v[68:69], v[30:31]
	v_pk_fma_f32 v[82:83], v[48:49], v[32:33], v[82:83]
	v_pk_fma_f32 v[86:87], v[70:71], v[32:33], v[86:87]
	v_pk_fma_f32 v[84:85], v[50:51], v[34:35], v[84:85]
	v_pk_fma_f32 v[88:89], v[72:73], v[34:35], v[88:89]
	v_pk_fma_f32 v[82:83], v[52:53], v[36:37], v[82:83]
	v_pk_fma_f32 v[86:87], v[74:75], v[36:37], v[86:87]
	v_pk_fma_f32 v[84:85], v[54:55], v[38:39], v[84:85]
	v_pk_fma_f32 v[88:89], v[76:77], v[38:39], v[88:89]
	v_pk_fma_f32 v[82:83], v[56:57], v[40:41], v[82:83]
	v_pk_fma_f32 v[86:87], v[78:79], v[40:41], v[86:87]
	v_pk_fma_f32 v[84:85], v[58:59], v[42:43], v[84:85]
	v_pk_fma_f32 v[88:89], v[80:81], v[42:43], v[88:89]
	v_pk_add_f32 v[82:83], v[82:83], v[84:85]
	v_pk_add_f32 v[86:87], v[86:87], v[88:89]
	v_lshl_add_u32 v11, v108, 10, v8
	v_add_f32_e32 v90, v82, v83
	v_add_f32_e32 v94, v86, v87
	global_load_dwordx4 v[180:183], v11, s[6:7]
	v_lshl_add_u32 v65, v109, 10, v8
	v_add_f32_dpp v91, v90, v90 quad_perm:[1,0,3,2] row_mask:0xf bank_mask:0xf
	v_add_f32_dpp v95, v94, v94 quad_perm:[1,0,3,2] row_mask:0xf bank_mask:0xf
	global_load_dwordx4 v[184:187], v65, s[6:7]
	v_add_f32_dpp v92, v91, v91 quad_perm:[2,3,0,1] row_mask:0xf bank_mask:0xf
	v_add_f32_dpp v96, v95, v95 quad_perm:[2,3,0,1] row_mask:0xf bank_mask:0xf
	s_nop 0
	v_add_f32_dpp v93, v92, v92 row_half_mirror row_mask:0xf bank_mask:0xf
	v_add_f32_dpp v97, v96, v96 row_half_mirror row_mask:0xf bank_mask:0xf
	v_fmac_f32_e32 v99, v93, v12
	v_fmac_f32_e32 v99, v97, v13
	s_waitcnt vmcnt(17)
	v_cvt_pk_f32_fp8_e32 v[44:45], v188
	v_cvt_pk_f32_fp8_sdwa v[46:47], v188 src0_sel:WORD_1
	v_cvt_pk_f32_fp8_e32 v[48:49], v189
	v_cvt_pk_f32_fp8_sdwa v[50:51], v189 src0_sel:WORD_1
	v_cvt_pk_f32_fp8_e32 v[52:53], v190
	v_cvt_pk_f32_fp8_sdwa v[54:55], v190 src0_sel:WORD_1
	v_cvt_pk_f32_fp8_e32 v[56:57], v191
	v_cvt_pk_f32_fp8_sdwa v[58:59], v191 src0_sel:WORD_1
	v_cvt_pk_f32_fp8_e32 v[66:67], v192
	v_cvt_pk_f32_fp8_sdwa v[68:69], v192 src0_sel:WORD_1
	v_cvt_pk_f32_fp8_e32 v[70:71], v193
	v_cvt_pk_f32_fp8_sdwa v[72:73], v193 src0_sel:WORD_1
	v_cvt_pk_f32_fp8_e32 v[74:75], v194
	v_cvt_pk_f32_fp8_sdwa v[76:77], v194 src0_sel:WORD_1
	v_cvt_pk_f32_fp8_e32 v[78:79], v195
	v_cvt_pk_f32_fp8_sdwa v[80:81], v195 src0_sel:WORD_1
	v_pk_mul_f32 v[82:83], v[44:45], v[28:29]
	v_pk_mul_f32 v[86:87], v[66:67], v[28:29]
	v_pk_mul_f32 v[84:85], v[46:47], v[30:31]
	v_pk_mul_f32 v[88:89], v[68:69], v[30:31]
	v_pk_fma_f32 v[82:83], v[48:49], v[32:33], v[82:83]
	v_pk_fma_f32 v[86:87], v[70:71], v[32:33], v[86:87]
	v_pk_fma_f32 v[84:85], v[50:51], v[34:35], v[84:85]
	v_pk_fma_f32 v[88:89], v[72:73], v[34:35], v[88:89]
	v_pk_fma_f32 v[82:83], v[52:53], v[36:37], v[82:83]
	v_pk_fma_f32 v[86:87], v[74:75], v[36:37], v[86:87]
	v_pk_fma_f32 v[84:85], v[54:55], v[38:39], v[84:85]
	v_pk_fma_f32 v[88:89], v[76:77], v[38:39], v[88:89]
	v_pk_fma_f32 v[82:83], v[56:57], v[40:41], v[82:83]
	v_pk_fma_f32 v[86:87], v[78:79], v[40:41], v[86:87]
	v_pk_fma_f32 v[84:85], v[58:59], v[42:43], v[84:85]
	v_pk_fma_f32 v[88:89], v[80:81], v[42:43], v[88:89]
	v_pk_add_f32 v[82:83], v[82:83], v[84:85]
	v_pk_add_f32 v[86:87], v[86:87], v[88:89]
	v_lshl_add_u32 v11, v110, 10, v8
	v_add_f32_e32 v90, v82, v83
	v_add_f32_e32 v94, v86, v87
	global_load_dwordx4 v[188:191], v11, s[6:7]
	v_lshl_add_u32 v65, v111, 10, v8
	v_add_f32_dpp v91, v90, v90 quad_perm:[1,0,3,2] row_mask:0xf bank_mask:0xf
	v_add_f32_dpp v95, v94, v94 quad_perm:[1,0,3,2] row_mask:0xf bank_mask:0xf
	global_load_dwordx4 v[192:195], v65, s[6:7]
	v_add_f32_dpp v92, v91, v91 quad_perm:[2,3,0,1] row_mask:0xf bank_mask:0xf
	v_add_f32_dpp v96, v95, v95 quad_perm:[2,3,0,1] row_mask:0xf bank_mask:0xf
	s_nop 0
	v_add_f32_dpp v93, v92, v92 row_half_mirror row_mask:0xf bank_mask:0xf
	v_add_f32_dpp v97, v96, v96 row_half_mirror row_mask:0xf bank_mask:0xf
	v_fmac_f32_e32 v99, v93, v14
	v_fmac_f32_e32 v99, v97, v15
	s_waitcnt vmcnt(17)
; DI void phase_peer_down(const Params& p) {
;     ...
;       for (int bi = 0; bi < 8; ++bi) {
;         u32x4 dr[8];
; #pragma unroll
;         for (int k = 0; k < 8; ++k) {
;           const int er = __builtin_amdgcn_readlane(ev, bi * 8 + k);
;           dr[k] = *reinterpret_cast<const u32x4*>(exd + (size_t)er * 1024 + lane * 16);
;         }
;         const int pmine = bi * 8 + (lane & 7);
;         const int emine = __shfl(ev, pmine);
;         const float gsel = __shfl(gv, pmine);
;         const float sd = esc[emine];
;         const float su = esc[16384 + emine];
;         float part[8];
; #pragma unroll
;         for (int k = 0; k < 8; ++k) {
;           float a0 = 0.f, a1 = 0.f;
; #pragma unroll
;           for (int w = 0; w < 4; ++w) {
;             f2_t lo = __builtin_amdgcn_cvt_pk_f32_fp8((int)dr[k][w], false);
;             f2_t hi = __builtin_amdgcn_cvt_pk_f32_fp8((int)dr[k][w], true);
;             a0 = fmaf(lo[0], x[4 * w], a0); a1 = fmaf(lo[1], x[4 * w + 1], a1);
;             a0 = fmaf(hi[0], x[4 * w + 2], a0); a1 = fmaf(hi[1], x[4 * w + 3], a1);
;           }
;           part[k] = a0 + a1;
;         }
;         const float r1 = reduce8(part, lane) * sd;
;         const bool mine = (lane >> 3) == bi;
;         racc = mine ? r1 : racc; gacc = mine ? gsel * su : gacc;
;       }
;       const float act = 0.5f * racc * (1.f + erff(racc * 0.70710678118654752f));
;       coefw[slot] = gacc * act;
	v_cvt_pk_f32_fp8_e32 v[44:45], v196
	v_cvt_pk_f32_fp8_sdwa v[46:47], v196 src0_sel:WORD_1
	v_cvt_pk_f32_fp8_e32 v[48:49], v197
	v_cvt_pk_f32_fp8_sdwa v[50:51], v197 src0_sel:WORD_1
	v_cvt_pk_f32_fp8_e32 v[52:53], v198
	v_cvt_pk_f32_fp8_sdwa v[54:55], v198 src0_sel:WORD_1
	v_cvt_pk_f32_fp8_e32 v[56:57], v199
	v_cvt_pk_f32_fp8_sdwa v[58:59], v199 src0_sel:WORD_1
	v_cvt_pk_f32_fp8_e32 v[66:67], v200
	v_cvt_pk_f32_fp8_sdwa v[68:69], v200 src0_sel:WORD_1
	v_cvt_pk_f32_fp8_e32 v[70:71], v201
	v_cvt_pk_f32_fp8_sdwa v[72:73], v201 src0_sel:WORD_1
	v_cvt_pk_f32_fp8_e32 v[74:75], v202
	v_cvt_pk_f32_fp8_sdwa v[76:77], v202 src0_sel:WORD_1
	v_cvt_pk_f32_fp8_e32 v[78:79], v203
	v_cvt_pk_f32_fp8_sdwa v[80:81], v203 src0_sel:WORD_1
	v_pk_mul_f32 v[82:83], v[44:45], v[28:29]
	v_pk_mul_f32 v[86:87], v[66:67], v[28:29]
	v_pk_mul_f32 v[84:85], v[46:47], v[30:31]
	v_pk_mul_f32 v[88:89], v[68:69], v[30:31]
	v_pk_fma_f32 v[82:83], v[48:49], v[32:33], v[82:83]
	v_pk_fma_f32 v[86:87], v[70:71], v[32:33], v[86:87]
	v_pk_fma_f32 v[84:85], v[50:51], v[34:35], v[84:85]
	v_pk_fma_f32 v[88:89], v[72:73], v[34:35], v[88:89]
	v_pk_fma_f32 v[82:83], v[52:53], v[36:37], v[82:83]
	v_pk_fma_f32 v[86:87], v[74:75], v[36:37], v[86:87]
	v_pk_fma_f32 v[84:85], v[54:55], v[38:39], v[84:85]
	v_pk_fma_f32 v[88:89], v[76:77], v[38:39], v[88:89]
	v_pk_fma_f32 v[82:83], v[56:57], v[40:41], v[82:83]
	v_pk_fma_f32 v[86:87], v[78:79], v[40:41], v[86:87]
	v_pk_fma_f32 v[84:85], v[58:59], v[42:43], v[84:85]
	v_pk_fma_f32 v[88:89], v[80:81], v[42:43], v[88:89]
	v_pk_add_f32 v[82:83], v[82:83], v[84:85]
	v_pk_add_f32 v[86:87], v[86:87], v[88:89]
	v_lshl_add_u32 v11, v112, 10, v8
	v_add_f32_e32 v90, v82, v83
	v_add_f32_e32 v94, v86, v87
	global_load_dwordx4 v[196:199], v11, s[6:7]
	v_lshl_add_u32 v65, v113, 10, v8
	v_add_f32_dpp v91, v90, v90 quad_perm:[1,0,3,2] row_mask:0xf bank_mask:0xf
	v_add_f32_dpp v95, v94, v94 quad_perm:[1,0,3,2] row_mask:0xf bank_mask:0xf
	global_load_dwordx4 v[200:203], v65, s[6:7]
	v_add_f32_dpp v92, v91, v91 quad_perm:[2,3,0,1] row_mask:0xf bank_mask:0xf
	v_add_f32_dpp v96, v95, v95 quad_perm:[2,3,0,1] row_mask:0xf bank_mask:0xf
	s_nop 0
	v_add_f32_dpp v93, v92, v92 row_half_mirror row_mask:0xf bank_mask:0xf
	v_add_f32_dpp v97, v96, v96 row_half_mirror row_mask:0xf bank_mask:0xf
	v_fmac_f32_e32 v99, v93, v16
	v_fmac_f32_e32 v99, v97, v17
	s_waitcnt vmcnt(17)
	v_cvt_pk_f32_fp8_e32 v[44:45], v204
	v_cvt_pk_f32_fp8_sdwa v[46:47], v204 src0_sel:WORD_1
	v_cvt_pk_f32_fp8_e32 v[48:49], v205
	v_cvt_pk_f32_fp8_sdwa v[50:51], v205 src0_sel:WORD_1
	v_cvt_pk_f32_fp8_e32 v[52:53], v206
	v_cvt_pk_f32_fp8_sdwa v[54:55], v206 src0_sel:WORD_1
	v_cvt_pk_f32_fp8_e32 v[56:57], v207
	v_cvt_pk_f32_fp8_sdwa v[58:59], v207 src0_sel:WORD_1
	v_cvt_pk_f32_fp8_e32 v[66:67], v208
	v_cvt_pk_f32_fp8_sdwa v[68:69], v208 src0_sel:WORD_1
	v_cvt_pk_f32_fp8_e32 v[70:71], v209
	v_cvt_pk_f32_fp8_sdwa v[72:73], v209 src0_sel:WORD_1
	v_cvt_pk_f32_fp8_e32 v[74:75], v210
	v_cvt_pk_f32_fp8_sdwa v[76:77], v210 src0_sel:WORD_1
	v_cvt_pk_f32_fp8_e32 v[78:79], v211
	v_cvt_pk_f32_fp8_sdwa v[80:81], v211 src0_sel:WORD_1
	v_pk_mul_f32 v[82:83], v[44:45], v[28:29]
	v_pk_mul_f32 v[86:87], v[66:67], v[28:29]
	v_pk_mul_f32 v[84:85], v[46:47], v[30:31]
	v_pk_mul_f32 v[88:89], v[68:69], v[30:31]
	v_pk_fma_f32 v[82:83], v[48:49], v[32:33], v[82:83]
	v_pk_fma_f32 v[86:87], v[70:71], v[32:33], v[86:87]
	v_pk_fma_f32 v[84:85], v[50:51], v[34:35], v[84:85]
	v_pk_fma_f32 v[88:89], v[72:73], v[34:35], v[88:89]
	v_pk_fma_f32 v[82:83], v[52:53], v[36:37], v[82:83]
	v_pk_fma_f32 v[86:87], v[74:75], v[36:37], v[86:87]
	v_pk_fma_f32 v[84:85], v[54:55], v[38:39], v[84:85]
	v_pk_fma_f32 v[88:89], v[76:77], v[38:39], v[88:89]
	v_pk_fma_f32 v[82:83], v[56:57], v[40:41], v[82:83]
	v_pk_fma_f32 v[86:87], v[78:79], v[40:41], v[86:87]
	v_pk_fma_f32 v[84:85], v[58:59], v[42:43], v[84:85]
	v_pk_fma_f32 v[88:89], v[80:81], v[42:43], v[88:89]
	v_pk_add_f32 v[82:83], v[82:83], v[84:85]
	v_pk_add_f32 v[86:87], v[86:87], v[88:89]
	v_lshl_add_u32 v11, v114, 10, v8
	v_add_f32_e32 v90, v82, v83
	v_add_f32_e32 v94, v86, v87
	global_load_dwordx4 v[204:207], v11, s[6:7]
	v_lshl_add_u32 v65, v115, 10, v8
	v_add_f32_dpp v91, v90, v90 quad_perm:[1,0,3,2] row_mask:0xf bank_mask:0xf
	v_add_f32_dpp v95, v94, v94 quad_perm:[1,0,3,2] row_mask:0xf bank_mask:0xf
	global_load_dwordx4 v[208:211], v65, s[6:7]
	v_add_f32_dpp v92, v91, v91 quad_perm:[2,3,0,1] row_mask:0xf bank_mask:0xf
	v_add_f32_dpp v96, v95, v95 quad_perm:[2,3,0,1] row_mask:0xf bank_mask:0xf
	s_nop 0
	v_add_f32_dpp v93, v92, v92 row_half_mirror row_mask:0xf bank_mask:0xf
	v_add_f32_dpp v97, v96, v96 row_half_mirror row_mask:0xf bank_mask:0xf
	v_fmac_f32_e32 v99, v93, v18
	v_fmac_f32_e32 v99, v97, v19
	ds_write_b64 v10, v[98:99]
	s_add_i32 s18, s18, 1
	s_cmpk_lt_u32 s18, 0x80
	s_cbranch_scc1 .Lpd_loop
	s_waitcnt vmcnt(0) lgkmcnt(0)
	v_lshrrev_b32_e32 v3, 2, v2
	v_lshl_add_u32 v3, v1, 4, v3
	s_mov_b32 s18, 0
	s_mov_b32 s25, 0x378e98ab
	s_mov_b32 s26, 0x3b7cd369
	s_mov_b32 s27, 0xbcc618b2
	s_mov_b32 s28, 0x3dda74e4
	s_mov_b32 s29, 0x3f228afd
	s_mov_b32 s30, 0x3e03c728
	s_mov_b32 s31, 0xbfb8aa3b
	s_mov_b32 s36, 0x42ce8ed0
	s_mov_b32 s37, 0xc2b17218
	s_brev_b32 s38, -2
	v_mov_b32_e32 v90, 0x3ba10414
	v_mov_b32_e32 v91, 0xb9c68948
	v_mov_b32_e32 v92, 0x7f800000
; DI void phase_peer_down(const Params& p) {
;     ...
;         const int pmine = bi * 8 + (lane & 7);
;         const int emine = __shfl(ev, pmine);
;         const float gsel = __shfl(gv, pmine);
;         const float sd = esc[emine];
;         const float su = esc[16384 + emine];
;         float part[8];
; #pragma unroll
;         for (int k = 0; k < 8; ++k) {
;           float a0 = 0.f, a1 = 0.f;
; #pragma unroll
;           for (int w = 0; w < 4; ++w) {
;             f2_t lo = __builtin_amdgcn_cvt_pk_f32_fp8((int)dr[k][w], false);
;             f2_t hi = __builtin_amdgcn_cvt_pk_f32_fp8((int)dr[k][w], true);
;             a0 = fmaf(lo[0], x[4 * w], a0); a1 = fmaf(lo[1], x[4 * w + 1], a1);
;             a0 = fmaf(hi[0], x[4 * w + 2], a0); a1 = fmaf(hi[1], x[4 * w + 3], a1);
;           }
;           part[k] = a0 + a1;
;         }
;         const float r1 = reduce8(part, lane) * sd;
;         const bool mine = (lane >> 3) == bi;
;         racc = mine ? r1 : racc; gacc = mine ? gsel * su : gacc;
;       }
;       const float act = 0.5f * racc * (1.f + erff(racc * 0.70710678118654752f));
;       coefw[slot] = gacc * act;
.Lpd_epi:
	s_add_i32 s20, s18, 0
	s_lshl_b32 s21, s20, 11
	s_lshl_b32 s22, s20, 9
	v_add_u32_e32 v11, s21, v64
	v_lshl_add_u32 v116, v11, 9, v3
	v_add_u32_e32 v10, s22, v4
	ds_read_b64 v[100:101], v10
	global_load_dword v20, v116, s[4:5]
	global_load_dword v28, v116, s[4:5] offset:32
	global_load_dword v36, v116, s[14:15]
	global_load_dword v44, v116, s[14:15] offset:32
	s_add_i32 s20, s18, 1
	s_lshl_b32 s21, s20, 11
	s_lshl_b32 s22, s20, 9
	v_add_u32_e32 v11, s21, v64
	v_lshl_add_u32 v117, v11, 9, v3
	v_add_u32_e32 v10, s22, v4
	ds_read_b64 v[102:103], v10
	global_load_dword v21, v117, s[4:5]
	global_load_dword v29, v117, s[4:5] offset:32
	global_load_dword v37, v117, s[14:15]
	global_load_dword v45, v117, s[14:15] offset:32
	s_add_i32 s20, s18, 2
	s_lshl_b32 s21, s20, 11
	s_lshl_b32 s22, s20, 9
	v_add_u32_e32 v11, s21, v64
	v_lshl_add_u32 v118, v11, 9, v3
	v_add_u32_e32 v10, s22, v4
	ds_read_b64 v[104:105], v10
	global_load_dword v22, v118, s[4:5]
	global_load_dword v30, v118, s[4:5] offset:32
	global_load_dword v38, v118, s[14:15]
	global_load_dword v46, v118, s[14:15] offset:32
	s_add_i32 s20, s18, 3
	s_lshl_b32 s21, s20, 11
	s_lshl_b32 s22, s20, 9
	v_add_u32_e32 v11, s21, v64
	v_lshl_add_u32 v119, v11, 9, v3
	v_add_u32_e32 v10, s22, v4
	ds_read_b64 v[106:107], v10
	global_load_dword v23, v119, s[4:5]
	global_load_dword v31, v119, s[4:5] offset:32
	global_load_dword v39, v119, s[14:15]
	global_load_dword v47, v119, s[14:15] offset:32
	s_add_i32 s20, s18, 4
	s_lshl_b32 s21, s20, 11
	s_lshl_b32 s22, s20, 9
	v_add_u32_e32 v11, s21, v64
	v_lshl_add_u32 v120, v11, 9, v3
	v_add_u32_e32 v10, s22, v4
	ds_read_b64 v[108:109], v10
	global_load_dword v24, v120, s[4:5]
	global_load_dword v32, v120, s[4:5] offset:32
	global_load_dword v40, v120, s[14:15]
	global_load_dword v48, v120, s[14:15] offset:32
	s_add_i32 s20, s18, 5
	s_lshl_b32 s21, s20, 11
	s_lshl_b32 s22, s20, 9
	v_add_u32_e32 v11, s21, v64
	v_lshl_add_u32 v121, v11, 9, v3
	v_add_u32_e32 v10, s22, v4
	ds_read_b64 v[110:111], v10
	global_load_dword v25, v121, s[4:5]
	global_load_dword v33, v121, s[4:5] offset:32
	global_load_dword v41, v121, s[14:15]
	global_load_dword v49, v121, s[14:15] offset:32
	s_add_i32 s20, s18, 6
	s_lshl_b32 s21, s20, 11
	s_lshl_b32 s22, s20, 9
	v_add_u32_e32 v11, s21, v64
	v_lshl_add_u32 v122, v11, 9, v3
	v_add_u32_e32 v10, s22, v4
	ds_read_b64 v[112:113], v10
	global_load_dword v26, v122, s[4:5]
	global_load_dword v34, v122, s[4:5] offset:32
	global_load_dword v42, v122, s[14:15]
	global_load_dword v50, v122, s[14:15] offset:32
	s_add_i32 s20, s18, 7
	s_lshl_b32 s21, s20, 11
	s_lshl_b32 s22, s20, 9
	v_add_u32_e32 v11, s21, v64
	v_lshl_add_u32 v123, v11, 9, v3
	v_add_u32_e32 v10, s22, v4
	ds_read_b64 v[114:115], v10
	global_load_dword v27, v123, s[4:5]
	global_load_dword v35, v123, s[4:5] offset:32
	global_load_dword v43, v123, s[14:15]
	global_load_dword v51, v123, s[14:15] offset:32
	s_waitcnt vmcnt(0)
	v_lshlrev_b32_e32 v20, 2, v20
	v_lshlrev_b32_e32 v28, 2, v28
	global_load_dword v52, v20, s[12:13]
	global_load_dword v66, v28, s[12:13]
	global_load_dword v74, v20, s[34:35]
	global_load_dword v82, v28, s[34:35]
	v_lshlrev_b32_e32 v21, 2, v21
	v_lshlrev_b32_e32 v29, 2, v29
	global_load_dword v53, v21, s[12:13]
	global_load_dword v67, v29, s[12:13]
	global_load_dword v75, v21, s[34:35]
	global_load_dword v83, v29, s[34:35]
	v_lshlrev_b32_e32 v22, 2, v22
	v_lshlrev_b32_e32 v30, 2, v30
	global_load_dword v54, v22, s[12:13]
	global_load_dword v68, v30, s[12:13]
	global_load_dword v76, v22, s[34:35]
	global_load_dword v84, v30, s[34:35]
	v_lshlrev_b32_e32 v23, 2, v23
	v_lshlrev_b32_e32 v31, 2, v31
	global_load_dword v55, v23, s[12:13]
	global_load_dword v69, v31, s[12:13]
	global_load_dword v77, v23, s[34:35]
	global_load_dword v85, v31, s[34:35]
	v_lshlrev_b32_e32 v24, 2, v24
	v_lshlrev_b32_e32 v32, 2, v32
	global_load_dword v56, v24, s[12:13]
	global_load_dword v70, v32, s[12:13]
	global_load_dword v78, v24, s[34:35]
	global_load_dword v86, v32, s[34:35]
	v_lshlrev_b32_e32 v25, 2, v25
	v_lshlrev_b32_e32 v33, 2, v33
	global_load_dword v57, v25, s[12:13]
	global_load_dword v71, v33, s[12:13]
	global_load_dword v79, v25, s[34:35]
	global_load_dword v87, v33, s[34:35]
	v_lshlrev_b32_e32 v26, 2, v26
	v_lshlrev_b32_e32 v34, 2, v34
	global_load_dword v58, v26, s[12:13]
	global_load_dword v72, v34, s[12:13]
	global_load_dword v80, v26, s[34:35]
	global_load_dword v88, v34, s[34:35]
	v_lshlrev_b32_e32 v27, 2, v27
	v_lshlrev_b32_e32 v35, 2, v35
	global_load_dword v59, v27, s[12:13]
	global_load_dword v73, v35, s[12:13]
	global_load_dword v81, v27, s[34:35]
	global_load_dword v89, v35, s[34:35]
	s_waitcnt vmcnt(0) lgkmcnt(0)
	v_mul_f32_e32 v93, v100, v52
	v_mul_f32_e32 v99, v36, v74
	v_mul_f32_e32 v94, 0x3f3504f3, v93
	v_cmp_nlt_f32_e64 s[20:21], |v94|, 1.0
	s_and_saveexec_b64 s[22:23], s[20:21]
	s_xor_b64 s[20:21], exec, s[22:23]
	s_cbranch_execz .Lpd_erf_a1
	v_fma_f32 v95, |v94|, s25, v91
	v_fma_f32 v95, |v94|, v95, s26
	v_fma_f32 v95, |v94|, v95, s27
	v_fma_f32 v95, |v94|, v95, s28
	v_fma_f32 v95, |v94|, v95, s29
	v_fma_f32 v95, |v94|, v95, s30
	v_fma_f32 v95, |v94|, v95, |v94|
	v_mul_f32_e32 v96, 0xbfb8aa3b, v95
	v_fma_f32 v97, v95, s31, -v96
	v_rndne_f32_e32 v98, v96
	v_fmac_f32_e32 v97, 0xb2a5705f, v95
	v_sub_f32_e32 v96, v96, v98
	v_add_f32_e32 v96, v96, v97
	v_cvt_i32_f32_e32 v97, v98
	v_exp_f32_e32 v96, v96
	v_cmp_nlt_f32_e32 vcc, s36, v95
	v_ldexp_f32 v96, v96, v97
	s_nop 0
	v_cndmask_b32_e32 v96, 0, v96, vcc
	v_cmp_ngt_f32_e32 vcc, s37, v95
	s_nop 1
	v_cndmask_b32_e32 v95, v92, v96, vcc
	v_sub_f32_e32 v95, 1.0, v95

; DI void phase_peer_down(const Params& p) {
;     ...
;       const float act = 0.5f * racc * (1.f + erff(racc * 0.70710678118654752f));
;       coefw[slot] = gacc * act;
.Lpd_erf_b2:
	s_or_b64 exec, exec, s[20:21]
	v_bfi_b32 v94, s38, v95, v94
	v_mul_f32_e32 v93, 0.5, v93
	v_add_f32_e32 v94, 1.0, v94
	v_mul_f32_e32 v93, v93, v94
	v_mul_f32_e32 v93, v99, v93
	global_store_dword v116, v93, s[16:17] offset:32
	v_mul_f32_e32 v93, v102, v53
	v_mul_f32_e32 v99, v37, v75
	v_mul_f32_e32 v94, 0x3f3504f3, v93
	v_cmp_nlt_f32_e64 s[20:21], |v94|, 1.0
	s_and_saveexec_b64 s[22:23], s[20:21]
	s_xor_b64 s[20:21], exec, s[22:23]
	s_cbranch_execz .Lpd_erf_a3
	v_fma_f32 v95, |v94|, s25, v91
	v_fma_f32 v95, |v94|, v95, s26
	v_fma_f32 v95, |v94|, v95, s27
	v_fma_f32 v95, |v94|, v95, s28
	v_fma_f32 v95, |v94|, v95, s29
	v_fma_f32 v95, |v94|, v95, s30
	v_fma_f32 v95, |v94|, v95, |v94|
	v_mul_f32_e32 v96, 0xbfb8aa3b, v95
	v_fma_f32 v97, v95, s31, -v96
	v_rndne_f32_e32 v98, v96
	v_fmac_f32_e32 v97, 0xb2a5705f, v95
	v_sub_f32_e32 v96, v96, v98
	v_add_f32_e32 v96, v96, v97
	v_cvt_i32_f32_e32 v97, v98
	v_exp_f32_e32 v96, v96
	v_cmp_nlt_f32_e32 vcc, s36, v95
	v_ldexp_f32 v96, v96, v97
	s_nop 0
	v_cndmask_b32_e32 v96, 0, v96, vcc
	v_cmp_ngt_f32_e32 vcc, s37, v95
	s_nop 1
	v_cndmask_b32_e32 v95, v92, v96, vcc
	v_sub_f32_e32 v95, 1.0, v95

; DI void phase_peer_down(const Params& p) {
;     ...
;       const float act = 0.5f * racc * (1.f + erff(racc * 0.70710678118654752f));
;       coefw[slot] = gacc * act;
.Lpd_erf_b4:
	s_or_b64 exec, exec, s[20:21]
	v_bfi_b32 v94, s38, v95, v94
	v_mul_f32_e32 v93, 0.5, v93
	v_add_f32_e32 v94, 1.0, v94
	v_mul_f32_e32 v93, v93, v94
	v_mul_f32_e32 v93, v99, v93
	global_store_dword v117, v93, s[16:17] offset:32
	v_mul_f32_e32 v93, v104, v54
	v_mul_f32_e32 v99, v38, v76
	v_mul_f32_e32 v94, 0x3f3504f3, v93
	v_cmp_nlt_f32_e64 s[20:21], |v94|, 1.0
	s_and_saveexec_b64 s[22:23], s[20:21]
	s_xor_b64 s[20:21], exec, s[22:23]
	s_cbranch_execz .Lpd_erf_a5
	v_fma_f32 v95, |v94|, s25, v91
	v_fma_f32 v95, |v94|, v95, s26
	v_fma_f32 v95, |v94|, v95, s27
	v_fma_f32 v95, |v94|, v95, s28
	v_fma_f32 v95, |v94|, v95, s29
	v_fma_f32 v95, |v94|, v95, s30
	v_fma_f32 v95, |v94|, v95, |v94|
	v_mul_f32_e32 v96, 0xbfb8aa3b, v95
	v_fma_f32 v97, v95, s31, -v96
	v_rndne_f32_e32 v98, v96
	v_fmac_f32_e32 v97, 0xb2a5705f, v95
	v_sub_f32_e32 v96, v96, v98
	v_add_f32_e32 v96, v96, v97
	v_cvt_i32_f32_e32 v97, v98
	v_exp_f32_e32 v96, v96
	v_cmp_nlt_f32_e32 vcc, s36, v95
	v_ldexp_f32 v96, v96, v97
	s_nop 0
	v_cndmask_b32_e32 v96, 0, v96, vcc
	v_cmp_ngt_f32_e32 vcc, s37, v95
	s_nop 1
	v_cndmask_b32_e32 v95, v92, v96, vcc
	v_sub_f32_e32 v95, 1.0, v95

; DI void phase_peer_down(const Params& p) {
;     ...
;       const float act = 0.5f * racc * (1.f + erff(racc * 0.70710678118654752f));
;       coefw[slot] = gacc * act;
.Lpd_erf_b6:
	s_or_b64 exec, exec, s[20:21]
	v_bfi_b32 v94, s38, v95, v94
	v_mul_f32_e32 v93, 0.5, v93
	v_add_f32_e32 v94, 1.0, v94
	v_mul_f32_e32 v93, v93, v94
	v_mul_f32_e32 v93, v99, v93
	global_store_dword v118, v93, s[16:17] offset:32
	v_mul_f32_e32 v93, v106, v55
	v_mul_f32_e32 v99, v39, v77
	v_mul_f32_e32 v94, 0x3f3504f3, v93
	v_cmp_nlt_f32_e64 s[20:21], |v94|, 1.0
	s_and_saveexec_b64 s[22:23], s[20:21]
	s_xor_b64 s[20:21], exec, s[22:23]
	s_cbranch_execz .Lpd_erf_a7
	v_fma_f32 v95, |v94|, s25, v91
	v_fma_f32 v95, |v94|, v95, s26
	v_fma_f32 v95, |v94|, v95, s27
	v_fma_f32 v95, |v94|, v95, s28
	v_fma_f32 v95, |v94|, v95, s29
	v_fma_f32 v95, |v94|, v95, s30
	v_fma_f32 v95, |v94|, v95, |v94|
	v_mul_f32_e32 v96, 0xbfb8aa3b, v95
	v_fma_f32 v97, v95, s31, -v96
	v_rndne_f32_e32 v98, v96
	v_fmac_f32_e32 v97, 0xb2a5705f, v95
	v_sub_f32_e32 v96, v96, v98
	v_add_f32_e32 v96, v96, v97
	v_cvt_i32_f32_e32 v97, v98
	v_exp_f32_e32 v96, v96
	v_cmp_nlt_f32_e32 vcc, s36, v95
	v_ldexp_f32 v96, v96, v97
	s_nop 0
	v_cndmask_b32_e32 v96, 0, v96, vcc
	v_cmp_ngt_f32_e32 vcc, s37, v95
	s_nop 1
	v_cndmask_b32_e32 v95, v92, v96, vcc
	v_sub_f32_e32 v95, 1.0, v95

; DI void phase_peer_down(const Params& p) {
;     ...
;       const float act = 0.5f * racc * (1.f + erff(racc * 0.70710678118654752f));
;       coefw[slot] = gacc * act;
.Lpd_erf_b8:
	s_or_b64 exec, exec, s[20:21]
	v_bfi_b32 v94, s38, v95, v94
	v_mul_f32_e32 v93, 0.5, v93
	v_add_f32_e32 v94, 1.0, v94
	v_mul_f32_e32 v93, v93, v94
	v_mul_f32_e32 v93, v99, v93
	global_store_dword v119, v93, s[16:17] offset:32
	v_mul_f32_e32 v93, v108, v56
	v_mul_f32_e32 v99, v40, v78
	v_mul_f32_e32 v94, 0x3f3504f3, v93
	v_cmp_nlt_f32_e64 s[20:21], |v94|, 1.0
	s_and_saveexec_b64 s[22:23], s[20:21]
	s_xor_b64 s[20:21], exec, s[22:23]
	s_cbranch_execz .Lpd_erf_a9
	v_fma_f32 v95, |v94|, s25, v91
	v_fma_f32 v95, |v94|, v95, s26
	v_fma_f32 v95, |v94|, v95, s27
	v_fma_f32 v95, |v94|, v95, s28
	v_fma_f32 v95, |v94|, v95, s29
	v_fma_f32 v95, |v94|, v95, s30
	v_fma_f32 v95, |v94|, v95, |v94|
	v_mul_f32_e32 v96, 0xbfb8aa3b, v95
	v_fma_f32 v97, v95, s31, -v96
	v_rndne_f32_e32 v98, v96
	v_fmac_f32_e32 v97, 0xb2a5705f, v95
	v_sub_f32_e32 v96, v96, v98
	v_add_f32_e32 v96, v96, v97
	v_cvt_i32_f32_e32 v97, v98
	v_exp_f32_e32 v96, v96
	v_cmp_nlt_f32_e32 vcc, s36, v95
	v_ldexp_f32 v96, v96, v97
	s_nop 0
	v_cndmask_b32_e32 v96, 0, v96, vcc
	v_cmp_ngt_f32_e32 vcc, s37, v95
	s_nop 1
	v_cndmask_b32_e32 v95, v92, v96, vcc
	v_sub_f32_e32 v95, 1.0, v95

; DI void phase_peer_down(const Params& p) {
;     ...
;       const float act = 0.5f * racc * (1.f + erff(racc * 0.70710678118654752f));
;       coefw[slot] = gacc * act;
.Lpd_erf_b10:
	s_or_b64 exec, exec, s[20:21]
	v_bfi_b32 v94, s38, v95, v94
	v_mul_f32_e32 v93, 0.5, v93
	v_add_f32_e32 v94, 1.0, v94
	v_mul_f32_e32 v93, v93, v94
	v_mul_f32_e32 v93, v99, v93
	global_store_dword v120, v93, s[16:17] offset:32
	v_mul_f32_e32 v93, v110, v57
	v_mul_f32_e32 v99, v41, v79
	v_mul_f32_e32 v94, 0x3f3504f3, v93
	v_cmp_nlt_f32_e64 s[20:21], |v94|, 1.0
	s_and_saveexec_b64 s[22:23], s[20:21]
	s_xor_b64 s[20:21], exec, s[22:23]
	s_cbranch_execz .Lpd_erf_a11
	v_fma_f32 v95, |v94|, s25, v91
	v_fma_f32 v95, |v94|, v95, s26
	v_fma_f32 v95, |v94|, v95, s27
	v_fma_f32 v95, |v94|, v95, s28
	v_fma_f32 v95, |v94|, v95, s29
	v_fma_f32 v95, |v94|, v95, s30
	v_fma_f32 v95, |v94|, v95, |v94|
	v_mul_f32_e32 v96, 0xbfb8aa3b, v95
	v_fma_f32 v97, v95, s31, -v96
	v_rndne_f32_e32 v98, v96
	v_fmac_f32_e32 v97, 0xb2a5705f, v95
	v_sub_f32_e32 v96, v96, v98
	v_add_f32_e32 v96, v96, v97
	v_cvt_i32_f32_e32 v97, v98
	v_exp_f32_e32 v96, v96
	v_cmp_nlt_f32_e32 vcc, s36, v95
	v_ldexp_f32 v96, v96, v97
	s_nop 0
	v_cndmask_b32_e32 v96, 0, v96, vcc
	v_cmp_ngt_f32_e32 vcc, s37, v95
	s_nop 1
	v_cndmask_b32_e32 v95, v92, v96, vcc
	v_sub_f32_e32 v95, 1.0, v95

; DI void phase_peer_down(const Params& p) {
;     ...
;       const float act = 0.5f * racc * (1.f + erff(racc * 0.70710678118654752f));
;       coefw[slot] = gacc * act;
.Lpd_erf_b12:
	s_or_b64 exec, exec, s[20:21]
	v_bfi_b32 v94, s38, v95, v94
	v_mul_f32_e32 v93, 0.5, v93
	v_add_f32_e32 v94, 1.0, v94
	v_mul_f32_e32 v93, v93, v94
	v_mul_f32_e32 v93, v99, v93
	global_store_dword v121, v93, s[16:17] offset:32
	v_mul_f32_e32 v93, v112, v58
	v_mul_f32_e32 v99, v42, v80
	v_mul_f32_e32 v94, 0x3f3504f3, v93
	v_cmp_nlt_f32_e64 s[20:21], |v94|, 1.0
	s_and_saveexec_b64 s[22:23], s[20:21]
	s_xor_b64 s[20:21], exec, s[22:23]
	s_cbranch_execz .Lpd_erf_a13
	v_fma_f32 v95, |v94|, s25, v91
	v_fma_f32 v95, |v94|, v95, s26
	v_fma_f32 v95, |v94|, v95, s27
	v_fma_f32 v95, |v94|, v95, s28
	v_fma_f32 v95, |v94|, v95, s29
	v_fma_f32 v95, |v94|, v95, s30
	v_fma_f32 v95, |v94|, v95, |v94|
	v_mul_f32_e32 v96, 0xbfb8aa3b, v95
	v_fma_f32 v97, v95, s31, -v96
	v_rndne_f32_e32 v98, v96
	v_fmac_f32_e32 v97, 0xb2a5705f, v95
	v_sub_f32_e32 v96, v96, v98
	v_add_f32_e32 v96, v96, v97
	v_cvt_i32_f32_e32 v97, v98
	v_exp_f32_e32 v96, v96
	v_cmp_nlt_f32_e32 vcc, s36, v95
	v_ldexp_f32 v96, v96, v97
	s_nop 0
	v_cndmask_b32_e32 v96, 0, v96, vcc
	v_cmp_ngt_f32_e32 vcc, s37, v95
	s_nop 1
	v_cndmask_b32_e32 v95, v92, v96, vcc
	v_sub_f32_e32 v95, 1.0, v95

; DI void phase_peer_down(const Params& p) {
;     ...
;       const float act = 0.5f * racc * (1.f + erff(racc * 0.70710678118654752f));
;       coefw[slot] = gacc * act;
.Lpd_erf_b14:
	s_or_b64 exec, exec, s[20:21]
	v_bfi_b32 v94, s38, v95, v94
	v_mul_f32_e32 v93, 0.5, v93
	v_add_f32_e32 v94, 1.0, v94
	v_mul_f32_e32 v93, v93, v94
	v_mul_f32_e32 v93, v99, v93
	global_store_dword v122, v93, s[16:17] offset:32
	v_mul_f32_e32 v93, v114, v59
	v_mul_f32_e32 v99, v43, v81
	v_mul_f32_e32 v94, 0x3f3504f3, v93
	v_cmp_nlt_f32_e64 s[20:21], |v94|, 1.0
	s_and_saveexec_b64 s[22:23], s[20:21]
	s_xor_b64 s[20:21], exec, s[22:23]
	s_cbranch_execz .Lpd_erf_a15
	v_fma_f32 v95, |v94|, s25, v91
	v_fma_f32 v95, |v94|, v95, s26
	v_fma_f32 v95, |v94|, v95, s27
	v_fma_f32 v95, |v94|, v95, s28
	v_fma_f32 v95, |v94|, v95, s29
	v_fma_f32 v95, |v94|, v95, s30
	v_fma_f32 v95, |v94|, v95, |v94|
	v_mul_f32_e32 v96, 0xbfb8aa3b, v95
	v_fma_f32 v97, v95, s31, -v96
	v_rndne_f32_e32 v98, v96
	v_fmac_f32_e32 v97, 0xb2a5705f, v95
	v_sub_f32_e32 v96, v96, v98
	v_add_f32_e32 v96, v96, v97
	v_cvt_i32_f32_e32 v97, v98
	v_exp_f32_e32 v96, v96
	v_cmp_nlt_f32_e32 vcc, s36, v95
	v_ldexp_f32 v96, v96, v97
	s_nop 0
	v_cndmask_b32_e32 v96, 0, v96, vcc
	v_cmp_ngt_f32_e32 vcc, s37, v95
	s_nop 1
	v_cndmask_b32_e32 v95, v92, v96, vcc
	v_sub_f32_e32 v95, 1.0, v95

; DI void phase_peer_down(const Params& p) {
;     ...
;       const float act = 0.5f * racc * (1.f + erff(racc * 0.70710678118654752f));
;       coefw[slot] = gacc * act;
.Lpd_erf_b16:
	s_or_b64 exec, exec, s[20:21]
	v_bfi_b32 v94, s38, v95, v94
	v_mul_f32_e32 v93, 0.5, v93
	v_add_f32_e32 v94, 1.0, v94
	v_mul_f32_e32 v93, v93, v94
	v_mul_f32_e32 v93, v99, v93
	global_store_dword v123, v93, s[16:17] offset:32
	s_add_i32 s18, s18, 8
	s_cmpk_lt_u32 s18, 16
	s_cbranch_scc1 .Lpd_epi

; DI void phase_peer_ffn(const Params& p) {
;     ...
;   for (int tok = gw; tok < T_; tok += nw) {
;     float yacc[16];
; #pragma unroll
;     for (int i = 0; i < 16; ++i) yacc[i] = 0.f;
;     const int e_lo = eidx[(size_t)tok * 128 + lane];
;     const int e_hi = eidx[(size_t)tok * 128 + 64 + lane];
;     const float c_lo = coefw[(size_t)tok * 128 + lane];
;     const float c_hi = coefw[(size_t)tok * 128 + 64 + lane];
; #pragma unroll 1
;     for (int eb = 0; eb < 8; ++eb) {
;       const int ev = (eb < 4) ? e_lo : e_hi;
;       const float cv = (eb < 4) ? c_lo : c_hi;
;       const int lbase = (eb & 3) * 16;
;       u32x4 ur[16];
; #pragma unroll
;       for (int k = 0; k < 16; ++k) {
;         const int er = __builtin_amdgcn_readlane(ev, lbase + k);
;         ur[k] = *reinterpret_cast<const u32x4*>(exu + (size_t)er * 1024 + lane * 16);
;       }
; #pragma unroll
;       for (int k = 0; k < 16; ++k) {
;         const float ck = __int_as_float(__builtin_amdgcn_readlane(__float_as_int(cv), lbase + k));
; #pragma unroll
;         for (int w = 0; w < 4; ++w) {
;           f2_t lo = __builtin_amdgcn_cvt_pk_f32_fp8((int)ur[k][w], false);
;           f2_t hi = __builtin_amdgcn_cvt_pk_f32_fp8((int)ur[k][w], true);
;           yacc[4 * w] = fmaf(ck, lo[0], yacc[4 * w]);
;           yacc[4 * w + 1] = fmaf(ck, lo[1], yacc[4 * w + 1]);
;           yacc[4 * w + 2] = fmaf(ck, hi[0], yacc[4 * w + 2]);
;           yacc[4 * w + 3] = fmaf(ck, hi[1], yacc[4 * w + 3]);
;         }
;       }
.LBB0_1085:
	s_or_b64 exec, exec, s[4:5]
	s_waitcnt lgkmcnt(0)
	s_barrier
	s_and_saveexec_b64 s[4:5], s[2:3]
	s_cbranch_execz .LBB0_1090
	s_mov_b32 s2, s96
	s_mov_b32 s3, s97
	s_add_u32 s6, s96, 0x5000000
	s_addc_u32 s7, s97, 0
	s_add_u32 s8, s96, 0x2000000
	s_addc_u32 s9, s97, 0
	v_mbcnt_lo_u32_b32 v0, -1, 0
	v_mbcnt_hi_u32_b32 v0, -1, v0
	v_lshrrev_b32_e32 v1, 3, v0
	v_and_b32_e32 v2, 7, v0
	v_lshlrev_b32_e32 v2, 4, v2
	v_lshl_add_u32 v3, v1, 9, v2
	v_lshlrev_b32_e32 v1, 2, v1
	v_lshlrev_b32_e32 v4, 3, v0
	v_and_b32_e32 v5, 7, v64
	v_lshlrev_b32_e32 v5, 12, v5
	v_add_u32_e32 v3, v5, v3
	v_add_u32_e32 v4, v5, v4
	v_and_b32_e32 v5, 14, v0
	v_lshlrev_b32_e32 v5, 5, v5
	v_lshrrev_b32_e32 v6, 4, v0
	v_lshl_add_u32 v5, v6, 4, v5
	v_and_b32_e32 v6, 1, v0
	v_lshl_add_u32 v5, v6, 3, v5
	v_lshlrev_b32_e32 v148, 3, v0
	v_and_b32_e32 v149, 7, v64
	v_lshlrev_b32_e32 v149, 10, v149
	v_add_u32_e32 v149, 0x8000, v149
	v_lshl_add_u32 v150, v1, 4, v149
	v_add_u32_e32 v149, v148, v149
	v_lshl_add_u32 v9, v64, 9, v148
	global_load_dwordx2 v[152:153], v9, s[2:3]
	global_load_dwordx2 v[154:155], v9, s[8:9]
	s_waitcnt vmcnt(1)
	ds_write_b64 v149, v[152:153]
	ds_read_b128 v[100:103], v150 offset:0
	ds_read_b128 v[104:107], v150 offset:16
	ds_read_b128 v[108:111], v150 offset:32
	ds_read_b128 v[112:115], v150 offset:48
	v_add_u32_e32 v6, 0x800, v64
	v_lshl_add_u32 v9, v6, 9, v148
	global_load_dwordx2 v[152:153], v9, s[2:3]
	s_waitcnt lgkmcnt(0)
	v_lshl_add_u32 v11, v100, 10, v2
	global_load_dwordx4 v[180:183], v11, s[6:7]
	v_lshl_add_u32 v11, v101, 10, v2
	global_load_dwordx4 v[184:187], v11, s[6:7]
	v_lshl_add_u32 v11, v102, 10, v2
	global_load_dwordx4 v[188:191], v11, s[6:7]
	v_lshl_add_u32 v11, v103, 10, v2
	global_load_dwordx4 v[192:195], v11, s[6:7]
	v_lshl_add_u32 v11, v104, 10, v2
	global_load_dwordx4 v[196:199], v11, s[6:7]
	v_lshl_add_u32 v11, v105, 10, v2
	global_load_dwordx4 v[200:203], v11, s[6:7]
	v_lshl_add_u32 v11, v106, 10, v2
	global_load_dwordx4 v[204:207], v11, s[6:7]
	v_lshl_add_u32 v11, v107, 10, v2
	global_load_dwordx4 v[208:211], v11, s[6:7]
	v_lshl_add_u32 v11, v108, 10, v2
	global_load_dwordx4 v[212:215], v11, s[6:7]
	v_lshl_add_u32 v11, v109, 10, v2
	global_load_dwordx4 v[216:219], v11, s[6:7]
	v_lshl_add_u32 v11, v110, 10, v2
	global_load_dwordx4 v[220:223], v11, s[6:7]
	v_lshl_add_u32 v11, v111, 10, v2
	global_load_dwordx4 v[224:227], v11, s[6:7]
	v_lshl_add_u32 v11, v112, 10, v2
	global_load_dwordx4 v[228:231], v11, s[6:7]
	v_lshl_add_u32 v11, v113, 10, v2
	global_load_dwordx4 v[232:235], v11, s[6:7]
	v_lshl_add_u32 v11, v114, 10, v2
	global_load_dwordx4 v[236:239], v11, s[6:7]
	v_lshl_add_u32 v11, v115, 10, v2
	global_load_dwordx4 v[240:243], v11, s[6:7]
	v_lshl_add_u32 v12, v64, 12, v5
	global_store_dwordx2 v12, v[82:83], s[58:59]
	s_mov_b32 s18, 0
.Lpf_loop:
	s_add_i32 s20, s18, 1
	s_min_i32 s20, s20, 0x7f
	s_lshr_b32 s21, s20, 4
	s_and_b32 s22, s20, 15
	s_add_i32 s23, s18, 2
	s_min_i32 s23, s23, 0x7f
	s_and_b32 s24, s23, 15
	s_and_b32 s26, s18, 15
	s_lshr_b32 s27, s18, 4
	s_lshl_b32 s22, s22, 11
	s_lshl_b32 s24, s24, 11
	s_lshl_b32 s28, s21, 7
	s_lshl_b32 s26, s26, 11
	s_lshl_b32 s27, s27, 9
	v_add_u32_e32 v6, s22, v64
	v_add_u32_e32 v7, s24, v64
	v_add_u32_e32 v8, s28, v2
	v_lshl_add_u32 v10, v6, 9, v148
	v_lshl_add_u32 v9, v7, 9, v148
	v_add_u32_e32 v12, s26, v64
	v_lshl_add_u32 v12, v12, 12, v5
	v_add_u32_e32 v12, s27, v12
	s_waitcnt vmcnt(17)
	ds_write_b64 v149, v[152:153]
	ds_write_b64 v149, v[154:155] offset:512
	ds_read_b128 v[100:103], v150 offset:0
	ds_read_b128 v[104:107], v150 offset:16
	ds_read_b128 v[108:111], v150 offset:32
	ds_read_b128 v[112:115], v150 offset:48
	ds_read_b128 v[132:135], v150 offset:512
	ds_read_b128 v[136:139], v150 offset:528
	ds_read_b128 v[140:143], v150 offset:544
	ds_read_b128 v[144:147], v150 offset:560
	global_load_dwordx2 v[152:153], v9, s[2:3]
	global_load_dwordx2 v[154:155], v10, s[8:9]
	s_waitcnt lgkmcnt(0)
	s_waitcnt vmcnt(17)
	v_cvt_pk_f32_fp8_e32 v[44:45], v180
	v_cvt_pk_f32_fp8_sdwa v[46:47], v180 src0_sel:WORD_1
	v_cvt_pk_f32_fp8_e32 v[48:49], v181
	v_cvt_pk_f32_fp8_sdwa v[50:51], v181 src0_sel:WORD_1
	v_cvt_pk_f32_fp8_e32 v[52:53], v182
	v_cvt_pk_f32_fp8_sdwa v[54:55], v182 src0_sel:WORD_1
	v_cvt_pk_f32_fp8_e32 v[56:57], v183
	v_cvt_pk_f32_fp8_sdwa v[58:59], v183 src0_sel:WORD_1
	v_cvt_pk_f32_fp8_e32 v[66:67], v184
	v_cvt_pk_f32_fp8_sdwa v[68:69], v184 src0_sel:WORD_1
	v_cvt_pk_f32_fp8_e32 v[70:71], v185
	v_cvt_pk_f32_fp8_sdwa v[72:73], v185 src0_sel:WORD_1
	v_cvt_pk_f32_fp8_e32 v[74:75], v186
	v_cvt_pk_f32_fp8_sdwa v[76:77], v186 src0_sel:WORD_1
	v_cvt_pk_f32_fp8_e32 v[78:79], v187
	v_cvt_pk_f32_fp8_sdwa v[80:81], v187 src0_sel:WORD_1
	v_lshl_add_u32 v11, v100, 10, v8
	v_lshl_add_u32 v65, v101, 10, v8
	global_load_dwordx4 v[180:183], v11, s[6:7]
	global_load_dwordx4 v[184:187], v65, s[6:7]
	v_pk_mul_f32 v[20:21], v[44:45], v[132:133] op_sel_hi:[1,0]
	v_pk_mul_f32 v[22:23], v[46:47], v[132:133] op_sel_hi:[1,0]
	v_pk_mul_f32 v[24:25], v[48:49], v[132:133] op_sel_hi:[1,0]
	v_pk_mul_f32 v[26:27], v[50:51], v[132:133] op_sel_hi:[1,0]
	v_pk_mul_f32 v[28:29], v[52:53], v[132:133] op_sel_hi:[1,0]
	v_pk_mul_f32 v[30:31], v[54:55], v[132:133] op_sel_hi:[1,0]
	v_pk_mul_f32 v[32:33], v[56:57], v[132:133] op_sel_hi:[1,0]
	v_pk_mul_f32 v[34:35], v[58:59], v[132:133] op_sel_hi:[1,0]
	v_pk_fma_f32 v[20:21], v[66:67], v[132:133], v[20:21] op_sel:[0,1,0]
	v_pk_fma_f32 v[22:23], v[68:69], v[132:133], v[22:23] op_sel:[0,1,0]
	v_pk_fma_f32 v[24:25], v[70:71], v[132:133], v[24:25] op_sel:[0,1,0]
	v_pk_fma_f32 v[26:27], v[72:73], v[132:133], v[26:27] op_sel:[0,1,0]
	v_pk_fma_f32 v[28:29], v[74:75], v[132:133], v[28:29] op_sel:[0,1,0]
	v_pk_fma_f32 v[30:31], v[76:77], v[132:133], v[30:31] op_sel:[0,1,0]
	v_pk_fma_f32 v[32:33], v[78:79], v[132:133], v[32:33] op_sel:[0,1,0]
	v_pk_fma_f32 v[34:35], v[80:81], v[132:133], v[34:35] op_sel:[0,1,0]
	s_waitcnt vmcnt(17)
; DI void phase_peer_ffn(const Params& p) {
;     ...
; #pragma unroll
;       for (int k = 0; k < 16; ++k) {
;         const float ck = __int_as_float(__builtin_amdgcn_readlane(__float_as_int(cv), lbase + k));
; #pragma unroll
;         for (int w = 0; w < 4; ++w) {
;           f2_t lo = __builtin_amdgcn_cvt_pk_f32_fp8((int)ur[k][w], false);
;           f2_t hi = __builtin_amdgcn_cvt_pk_f32_fp8((int)ur[k][w], true);
;           yacc[4 * w] = fmaf(ck, lo[0], yacc[4 * w]);
;           yacc[4 * w + 1] = fmaf(ck, lo[1], yacc[4 * w + 1]);
;           yacc[4 * w + 2] = fmaf(ck, hi[0], yacc[4 * w + 2]);
;           yacc[4 * w + 3] = fmaf(ck, hi[1], yacc[4 * w + 3]);
;         }
;       }
	v_cvt_pk_f32_fp8_e32 v[44:45], v188
	v_cvt_pk_f32_fp8_sdwa v[46:47], v188 src0_sel:WORD_1
	v_cvt_pk_f32_fp8_e32 v[48:49], v189
	v_cvt_pk_f32_fp8_sdwa v[50:51], v189 src0_sel:WORD_1
	v_cvt_pk_f32_fp8_e32 v[52:53], v190
	v_cvt_pk_f32_fp8_sdwa v[54:55], v190 src0_sel:WORD_1
	v_cvt_pk_f32_fp8_e32 v[56:57], v191
	v_cvt_pk_f32_fp8_sdwa v[58:59], v191 src0_sel:WORD_1
	v_cvt_pk_f32_fp8_e32 v[66:67], v192
	v_cvt_pk_f32_fp8_sdwa v[68:69], v192 src0_sel:WORD_1
	v_cvt_pk_f32_fp8_e32 v[70:71], v193
	v_cvt_pk_f32_fp8_sdwa v[72:73], v193 src0_sel:WORD_1
	v_cvt_pk_f32_fp8_e32 v[74:75], v194
	v_cvt_pk_f32_fp8_sdwa v[76:77], v194 src0_sel:WORD_1
	v_cvt_pk_f32_fp8_e32 v[78:79], v195
	v_cvt_pk_f32_fp8_sdwa v[80:81], v195 src0_sel:WORD_1
	v_lshl_add_u32 v11, v102, 10, v8
	v_lshl_add_u32 v65, v103, 10, v8
	global_load_dwordx4 v[188:191], v11, s[6:7]
	global_load_dwordx4 v[192:195], v65, s[6:7]
	v_pk_fma_f32 v[20:21], v[44:45], v[134:135], v[20:21] op_sel_hi:[1,0,1]
	v_pk_fma_f32 v[22:23], v[46:47], v[134:135], v[22:23] op_sel_hi:[1,0,1]
	v_pk_fma_f32 v[24:25], v[48:49], v[134:135], v[24:25] op_sel_hi:[1,0,1]
	v_pk_fma_f32 v[26:27], v[50:51], v[134:135], v[26:27] op_sel_hi:[1,0,1]
	v_pk_fma_f32 v[28:29], v[52:53], v[134:135], v[28:29] op_sel_hi:[1,0,1]
	v_pk_fma_f32 v[30:31], v[54:55], v[134:135], v[30:31] op_sel_hi:[1,0,1]
	v_pk_fma_f32 v[32:33], v[56:57], v[134:135], v[32:33] op_sel_hi:[1,0,1]
	v_pk_fma_f32 v[34:35], v[58:59], v[134:135], v[34:35] op_sel_hi:[1,0,1]
	v_pk_fma_f32 v[20:21], v[66:67], v[134:135], v[20:21] op_sel:[0,1,0]
	v_pk_fma_f32 v[22:23], v[68:69], v[134:135], v[22:23] op_sel:[0,1,0]
	v_pk_fma_f32 v[24:25], v[70:71], v[134:135], v[24:25] op_sel:[0,1,0]
	v_pk_fma_f32 v[26:27], v[72:73], v[134:135], v[26:27] op_sel:[0,1,0]
	v_pk_fma_f32 v[28:29], v[74:75], v[134:135], v[28:29] op_sel:[0,1,0]
	v_pk_fma_f32 v[30:31], v[76:77], v[134:135], v[30:31] op_sel:[0,1,0]
	v_pk_fma_f32 v[32:33], v[78:79], v[134:135], v[32:33] op_sel:[0,1,0]
	v_pk_fma_f32 v[34:35], v[80:81], v[134:135], v[34:35] op_sel:[0,1,0]
	s_waitcnt vmcnt(17)
	v_cvt_pk_f32_fp8_e32 v[44:45], v196
	v_cvt_pk_f32_fp8_sdwa v[46:47], v196 src0_sel:WORD_1
	v_cvt_pk_f32_fp8_e32 v[48:49], v197
	v_cvt_pk_f32_fp8_sdwa v[50:51], v197 src0_sel:WORD_1
	v_cvt_pk_f32_fp8_e32 v[52:53], v198
	v_cvt_pk_f32_fp8_sdwa v[54:55], v198 src0_sel:WORD_1
	v_cvt_pk_f32_fp8_e32 v[56:57], v199
	v_cvt_pk_f32_fp8_sdwa v[58:59], v199 src0_sel:WORD_1
	v_cvt_pk_f32_fp8_e32 v[66:67], v200
	v_cvt_pk_f32_fp8_sdwa v[68:69], v200 src0_sel:WORD_1
	v_cvt_pk_f32_fp8_e32 v[70:71], v201
	v_cvt_pk_f32_fp8_sdwa v[72:73], v201 src0_sel:WORD_1
	v_cvt_pk_f32_fp8_e32 v[74:75], v202
	v_cvt_pk_f32_fp8_sdwa v[76:77], v202 src0_sel:WORD_1
	v_cvt_pk_f32_fp8_e32 v[78:79], v203
	v_cvt_pk_f32_fp8_sdwa v[80:81], v203 src0_sel:WORD_1
	v_lshl_add_u32 v11, v104, 10, v8
	v_lshl_add_u32 v65, v105, 10, v8
	global_load_dwordx4 v[196:199], v11, s[6:7]
	global_load_dwordx4 v[200:203], v65, s[6:7]
	v_pk_fma_f32 v[20:21], v[44:45], v[136:137], v[20:21] op_sel_hi:[1,0,1]
	v_pk_fma_f32 v[22:23], v[46:47], v[136:137], v[22:23] op_sel_hi:[1,0,1]
	v_pk_fma_f32 v[24:25], v[48:49], v[136:137], v[24:25] op_sel_hi:[1,0,1]
	v_pk_fma_f32 v[26:27], v[50:51], v[136:137], v[26:27] op_sel_hi:[1,0,1]
	v_pk_fma_f32 v[28:29], v[52:53], v[136:137], v[28:29] op_sel_hi:[1,0,1]
	v_pk_fma_f32 v[30:31], v[54:55], v[136:137], v[30:31] op_sel_hi:[1,0,1]
	v_pk_fma_f32 v[32:33], v[56:57], v[136:137], v[32:33] op_sel_hi:[1,0,1]
	v_pk_fma_f32 v[34:35], v[58:59], v[136:137], v[34:35] op_sel_hi:[1,0,1]
	v_pk_fma_f32 v[20:21], v[66:67], v[136:137], v[20:21] op_sel:[0,1,0]
	v_pk_fma_f32 v[22:23], v[68:69], v[136:137], v[22:23] op_sel:[0,1,0]
	v_pk_fma_f32 v[24:25], v[70:71], v[136:137], v[24:25] op_sel:[0,1,0]
	v_pk_fma_f32 v[26:27], v[72:73], v[136:137], v[26:27] op_sel:[0,1,0]
	v_pk_fma_f32 v[28:29], v[74:75], v[136:137], v[28:29] op_sel:[0,1,0]
	v_pk_fma_f32 v[30:31], v[76:77], v[136:137], v[30:31] op_sel:[0,1,0]
	v_pk_fma_f32 v[32:33], v[78:79], v[136:137], v[32:33] op_sel:[0,1,0]
	v_pk_fma_f32 v[34:35], v[80:81], v[136:137], v[34:35] op_sel:[0,1,0]
	s_waitcnt vmcnt(17)
	v_cvt_pk_f32_fp8_e32 v[44:45], v204
	v_cvt_pk_f32_fp8_sdwa v[46:47], v204 src0_sel:WORD_1
	v_cvt_pk_f32_fp8_e32 v[48:49], v205
	v_cvt_pk_f32_fp8_sdwa v[50:51], v205 src0_sel:WORD_1
	v_cvt_pk_f32_fp8_e32 v[52:53], v206
	v_cvt_pk_f32_fp8_sdwa v[54:55], v206 src0_sel:WORD_1
	v_cvt_pk_f32_fp8_e32 v[56:57], v207
	v_cvt_pk_f32_fp8_sdwa v[58:59], v207 src0_sel:WORD_1
	v_cvt_pk_f32_fp8_e32 v[66:67], v208
	v_cvt_pk_f32_fp8_sdwa v[68:69], v208 src0_sel:WORD_1
	v_cvt_pk_f32_fp8_e32 v[70:71], v209
	v_cvt_pk_f32_fp8_sdwa v[72:73], v209 src0_sel:WORD_1
	v_cvt_pk_f32_fp8_e32 v[74:75], v210
	v_cvt_pk_f32_fp8_sdwa v[76:77], v210 src0_sel:WORD_1
	v_cvt_pk_f32_fp8_e32 v[78:79], v211
	v_cvt_pk_f32_fp8_sdwa v[80:81], v211 src0_sel:WORD_1
	v_lshl_add_u32 v11, v106, 10, v8
	v_lshl_add_u32 v65, v107, 10, v8
	global_load_dwordx4 v[204:207], v11, s[6:7]
	global_load_dwordx4 v[208:211], v65, s[6:7]
	v_pk_fma_f32 v[20:21], v[44:45], v[138:139], v[20:21] op_sel_hi:[1,0,1]
	v_pk_fma_f32 v[22:23], v[46:47], v[138:139], v[22:23] op_sel_hi:[1,0,1]
	v_pk_fma_f32 v[24:25], v[48:49], v[138:139], v[24:25] op_sel_hi:[1,0,1]
	v_pk_fma_f32 v[26:27], v[50:51], v[138:139], v[26:27] op_sel_hi:[1,0,1]
	v_pk_fma_f32 v[28:29], v[52:53], v[138:139], v[28:29] op_sel_hi:[1,0,1]
	v_pk_fma_f32 v[30:31], v[54:55], v[138:139], v[30:31] op_sel_hi:[1,0,1]
	v_pk_fma_f32 v[32:33], v[56:57], v[138:139], v[32:33] op_sel_hi:[1,0,1]
	v_pk_fma_f32 v[34:35], v[58:59], v[138:139], v[34:35] op_sel_hi:[1,0,1]
	v_pk_fma_f32 v[20:21], v[66:67], v[138:139], v[20:21] op_sel:[0,1,0]
	v_pk_fma_f32 v[22:23], v[68:69], v[138:139], v[22:23] op_sel:[0,1,0]
	v_pk_fma_f32 v[24:25], v[70:71], v[138:139], v[24:25] op_sel:[0,1,0]
	v_pk_fma_f32 v[26:27], v[72:73], v[138:139], v[26:27] op_sel:[0,1,0]
	v_pk_fma_f32 v[28:29], v[74:75], v[138:139], v[28:29] op_sel:[0,1,0]
	v_pk_fma_f32 v[30:31], v[76:77], v[138:139], v[30:31] op_sel:[0,1,0]
	v_pk_fma_f32 v[32:33], v[78:79], v[138:139], v[32:33] op_sel:[0,1,0]
	v_pk_fma_f32 v[34:35], v[80:81], v[138:139], v[34:35] op_sel:[0,1,0]
	s_waitcnt vmcnt(17)
; DI void phase_peer_ffn(const Params& p) {
;     ...
; #pragma unroll
;       for (int k = 0; k < 16; ++k) {
;         const float ck = __int_as_float(__builtin_amdgcn_readlane(__float_as_int(cv), lbase + k));
; #pragma unroll
;         for (int w = 0; w < 4; ++w) {
;           f2_t lo = __builtin_amdgcn_cvt_pk_f32_fp8((int)ur[k][w], false);
;           f2_t hi = __builtin_amdgcn_cvt_pk_f32_fp8((int)ur[k][w], true);
;           yacc[4 * w] = fmaf(ck, lo[0], yacc[4 * w]);
;           yacc[4 * w + 1] = fmaf(ck, lo[1], yacc[4 * w + 1]);
;           yacc[4 * w + 2] = fmaf(ck, hi[0], yacc[4 * w + 2]);
;           yacc[4 * w + 3] = fmaf(ck, hi[1], yacc[4 * w + 3]);
;         }
;       }
	v_cvt_pk_f32_fp8_e32 v[44:45], v212
	v_cvt_pk_f32_fp8_sdwa v[46:47], v212 src0_sel:WORD_1
	v_cvt_pk_f32_fp8_e32 v[48:49], v213
	v_cvt_pk_f32_fp8_sdwa v[50:51], v213 src0_sel:WORD_1
	v_cvt_pk_f32_fp8_e32 v[52:53], v214
	v_cvt_pk_f32_fp8_sdwa v[54:55], v214 src0_sel:WORD_1
	v_cvt_pk_f32_fp8_e32 v[56:57], v215
	v_cvt_pk_f32_fp8_sdwa v[58:59], v215 src0_sel:WORD_1
	v_cvt_pk_f32_fp8_e32 v[66:67], v216
	v_cvt_pk_f32_fp8_sdwa v[68:69], v216 src0_sel:WORD_1
	v_cvt_pk_f32_fp8_e32 v[70:71], v217
	v_cvt_pk_f32_fp8_sdwa v[72:73], v217 src0_sel:WORD_1
	v_cvt_pk_f32_fp8_e32 v[74:75], v218
	v_cvt_pk_f32_fp8_sdwa v[76:77], v218 src0_sel:WORD_1
	v_cvt_pk_f32_fp8_e32 v[78:79], v219
	v_cvt_pk_f32_fp8_sdwa v[80:81], v219 src0_sel:WORD_1
	v_lshl_add_u32 v11, v108, 10, v8
	v_lshl_add_u32 v65, v109, 10, v8
	global_load_dwordx4 v[212:215], v11, s[6:7]
	global_load_dwordx4 v[216:219], v65, s[6:7]
	v_pk_fma_f32 v[20:21], v[44:45], v[140:141], v[20:21] op_sel_hi:[1,0,1]
	v_pk_fma_f32 v[22:23], v[46:47], v[140:141], v[22:23] op_sel_hi:[1,0,1]
	v_pk_fma_f32 v[24:25], v[48:49], v[140:141], v[24:25] op_sel_hi:[1,0,1]
	v_pk_fma_f32 v[26:27], v[50:51], v[140:141], v[26:27] op_sel_hi:[1,0,1]
	v_pk_fma_f32 v[28:29], v[52:53], v[140:141], v[28:29] op_sel_hi:[1,0,1]
	v_pk_fma_f32 v[30:31], v[54:55], v[140:141], v[30:31] op_sel_hi:[1,0,1]
	v_pk_fma_f32 v[32:33], v[56:57], v[140:141], v[32:33] op_sel_hi:[1,0,1]
	v_pk_fma_f32 v[34:35], v[58:59], v[140:141], v[34:35] op_sel_hi:[1,0,1]
	v_pk_fma_f32 v[20:21], v[66:67], v[140:141], v[20:21] op_sel:[0,1,0]
	v_pk_fma_f32 v[22:23], v[68:69], v[140:141], v[22:23] op_sel:[0,1,0]
	v_pk_fma_f32 v[24:25], v[70:71], v[140:141], v[24:25] op_sel:[0,1,0]
	v_pk_fma_f32 v[26:27], v[72:73], v[140:141], v[26:27] op_sel:[0,1,0]
	v_pk_fma_f32 v[28:29], v[74:75], v[140:141], v[28:29] op_sel:[0,1,0]
	v_pk_fma_f32 v[30:31], v[76:77], v[140:141], v[30:31] op_sel:[0,1,0]
	v_pk_fma_f32 v[32:33], v[78:79], v[140:141], v[32:33] op_sel:[0,1,0]
	v_pk_fma_f32 v[34:35], v[80:81], v[140:141], v[34:35] op_sel:[0,1,0]
	s_waitcnt vmcnt(17)
	v_cvt_pk_f32_fp8_e32 v[44:45], v220
	v_cvt_pk_f32_fp8_sdwa v[46:47], v220 src0_sel:WORD_1
	v_cvt_pk_f32_fp8_e32 v[48:49], v221
	v_cvt_pk_f32_fp8_sdwa v[50:51], v221 src0_sel:WORD_1
	v_cvt_pk_f32_fp8_e32 v[52:53], v222
	v_cvt_pk_f32_fp8_sdwa v[54:55], v222 src0_sel:WORD_1
	v_cvt_pk_f32_fp8_e32 v[56:57], v223
	v_cvt_pk_f32_fp8_sdwa v[58:59], v223 src0_sel:WORD_1
	v_cvt_pk_f32_fp8_e32 v[66:67], v224
	v_cvt_pk_f32_fp8_sdwa v[68:69], v224 src0_sel:WORD_1
	v_cvt_pk_f32_fp8_e32 v[70:71], v225
	v_cvt_pk_f32_fp8_sdwa v[72:73], v225 src0_sel:WORD_1
	v_cvt_pk_f32_fp8_e32 v[74:75], v226
	v_cvt_pk_f32_fp8_sdwa v[76:77], v226 src0_sel:WORD_1
	v_cvt_pk_f32_fp8_e32 v[78:79], v227
	v_cvt_pk_f32_fp8_sdwa v[80:81], v227 src0_sel:WORD_1
	v_lshl_add_u32 v11, v110, 10, v8
	v_lshl_add_u32 v65, v111, 10, v8
	global_load_dwordx4 v[220:223], v11, s[6:7]
	global_load_dwordx4 v[224:227], v65, s[6:7]
	v_pk_fma_f32 v[20:21], v[44:45], v[142:143], v[20:21] op_sel_hi:[1,0,1]
	v_pk_fma_f32 v[22:23], v[46:47], v[142:143], v[22:23] op_sel_hi:[1,0,1]
	v_pk_fma_f32 v[24:25], v[48:49], v[142:143], v[24:25] op_sel_hi:[1,0,1]
	v_pk_fma_f32 v[26:27], v[50:51], v[142:143], v[26:27] op_sel_hi:[1,0,1]
	v_pk_fma_f32 v[28:29], v[52:53], v[142:143], v[28:29] op_sel_hi:[1,0,1]
	v_pk_fma_f32 v[30:31], v[54:55], v[142:143], v[30:31] op_sel_hi:[1,0,1]
	v_pk_fma_f32 v[32:33], v[56:57], v[142:143], v[32:33] op_sel_hi:[1,0,1]
	v_pk_fma_f32 v[34:35], v[58:59], v[142:143], v[34:35] op_sel_hi:[1,0,1]
	v_pk_fma_f32 v[20:21], v[66:67], v[142:143], v[20:21] op_sel:[0,1,0]
	v_pk_fma_f32 v[22:23], v[68:69], v[142:143], v[22:23] op_sel:[0,1,0]
	v_pk_fma_f32 v[24:25], v[70:71], v[142:143], v[24:25] op_sel:[0,1,0]
	v_pk_fma_f32 v[26:27], v[72:73], v[142:143], v[26:27] op_sel:[0,1,0]
	v_pk_fma_f32 v[28:29], v[74:75], v[142:143], v[28:29] op_sel:[0,1,0]
	v_pk_fma_f32 v[30:31], v[76:77], v[142:143], v[30:31] op_sel:[0,1,0]
	v_pk_fma_f32 v[32:33], v[78:79], v[142:143], v[32:33] op_sel:[0,1,0]
	v_pk_fma_f32 v[34:35], v[80:81], v[142:143], v[34:35] op_sel:[0,1,0]
	s_waitcnt vmcnt(17)
	v_cvt_pk_f32_fp8_e32 v[44:45], v228
	v_cvt_pk_f32_fp8_sdwa v[46:47], v228 src0_sel:WORD_1
	v_cvt_pk_f32_fp8_e32 v[48:49], v229
	v_cvt_pk_f32_fp8_sdwa v[50:51], v229 src0_sel:WORD_1
	v_cvt_pk_f32_fp8_e32 v[52:53], v230
	v_cvt_pk_f32_fp8_sdwa v[54:55], v230 src0_sel:WORD_1
	v_cvt_pk_f32_fp8_e32 v[56:57], v231
	v_cvt_pk_f32_fp8_sdwa v[58:59], v231 src0_sel:WORD_1
	v_cvt_pk_f32_fp8_e32 v[66:67], v232
	v_cvt_pk_f32_fp8_sdwa v[68:69], v232 src0_sel:WORD_1
	v_cvt_pk_f32_fp8_e32 v[70:71], v233
	v_cvt_pk_f32_fp8_sdwa v[72:73], v233 src0_sel:WORD_1
	v_cvt_pk_f32_fp8_e32 v[74:75], v234
	v_cvt_pk_f32_fp8_sdwa v[76:77], v234 src0_sel:WORD_1
	v_cvt_pk_f32_fp8_e32 v[78:79], v235
	v_cvt_pk_f32_fp8_sdwa v[80:81], v235 src0_sel:WORD_1
	v_lshl_add_u32 v11, v112, 10, v8
	v_lshl_add_u32 v65, v113, 10, v8
	global_load_dwordx4 v[228:231], v11, s[6:7]
	global_load_dwordx4 v[232:235], v65, s[6:7]
	v_pk_fma_f32 v[20:21], v[44:45], v[144:145], v[20:21] op_sel_hi:[1,0,1]
	v_pk_fma_f32 v[22:23], v[46:47], v[144:145], v[22:23] op_sel_hi:[1,0,1]
	v_pk_fma_f32 v[24:25], v[48:49], v[144:145], v[24:25] op_sel_hi:[1,0,1]
	v_pk_fma_f32 v[26:27], v[50:51], v[144:145], v[26:27] op_sel_hi:[1,0,1]
	v_pk_fma_f32 v[28:29], v[52:53], v[144:145], v[28:29] op_sel_hi:[1,0,1]
	v_pk_fma_f32 v[30:31], v[54:55], v[144:145], v[30:31] op_sel_hi:[1,0,1]
	v_pk_fma_f32 v[32:33], v[56:57], v[144:145], v[32:33] op_sel_hi:[1,0,1]
	v_pk_fma_f32 v[34:35], v[58:59], v[144:145], v[34:35] op_sel_hi:[1,0,1]
	v_pk_fma_f32 v[20:21], v[66:67], v[144:145], v[20:21] op_sel:[0,1,0]
	v_pk_fma_f32 v[22:23], v[68:69], v[144:145], v[22:23] op_sel:[0,1,0]
	v_pk_fma_f32 v[24:25], v[70:71], v[144:145], v[24:25] op_sel:[0,1,0]
	v_pk_fma_f32 v[26:27], v[72:73], v[144:145], v[26:27] op_sel:[0,1,0]
	v_pk_fma_f32 v[28:29], v[74:75], v[144:145], v[28:29] op_sel:[0,1,0]
	v_pk_fma_f32 v[30:31], v[76:77], v[144:145], v[30:31] op_sel:[0,1,0]
	v_pk_fma_f32 v[32:33], v[78:79], v[144:145], v[32:33] op_sel:[0,1,0]
	v_pk_fma_f32 v[34:35], v[80:81], v[144:145], v[34:35] op_sel:[0,1,0]
	s_waitcnt vmcnt(17)
; DI void phase_peer_ffn(const Params& p) {
;     ...
;     const int e_lo = eidx[(size_t)tok * 128 + lane];
;     const int e_hi = eidx[(size_t)tok * 128 + 64 + lane];
;     const float c_lo = coefw[(size_t)tok * 128 + lane];
;     const float c_hi = coefw[(size_t)tok * 128 + 64 + lane];
;     ...
;       for (int k = 0; k < 16; ++k) {
;         const int er = __builtin_amdgcn_readlane(ev, lbase + k);
;         ur[k] = *reinterpret_cast<const u32x4*>(exu + (size_t)er * 1024 + lane * 16);
;       }
; #pragma unroll
;       for (int k = 0; k < 16; ++k) {
;         const float ck = __int_as_float(__builtin_amdgcn_readlane(__float_as_int(cv), lbase + k));
; #pragma unroll
;         for (int w = 0; w < 4; ++w) {
;           f2_t lo = __builtin_amdgcn_cvt_pk_f32_fp8((int)ur[k][w], false);
;           f2_t hi = __builtin_amdgcn_cvt_pk_f32_fp8((int)ur[k][w], true);
;           yacc[4 * w] = fmaf(ck, lo[0], yacc[4 * w]);
;           yacc[4 * w + 1] = fmaf(ck, lo[1], yacc[4 * w + 1]);
;           yacc[4 * w + 2] = fmaf(ck, hi[0], yacc[4 * w + 2]);
;           yacc[4 * w + 3] = fmaf(ck, hi[1], yacc[4 * w + 3]);
;         }
;       }
	v_cvt_pk_f32_fp8_e32 v[44:45], v236
	v_cvt_pk_f32_fp8_sdwa v[46:47], v236 src0_sel:WORD_1
	v_cvt_pk_f32_fp8_e32 v[48:49], v237
	v_cvt_pk_f32_fp8_sdwa v[50:51], v237 src0_sel:WORD_1
	v_cvt_pk_f32_fp8_e32 v[52:53], v238
	v_cvt_pk_f32_fp8_sdwa v[54:55], v238 src0_sel:WORD_1
	v_cvt_pk_f32_fp8_e32 v[56:57], v239
	v_cvt_pk_f32_fp8_sdwa v[58:59], v239 src0_sel:WORD_1
	v_cvt_pk_f32_fp8_e32 v[66:67], v240
	v_cvt_pk_f32_fp8_sdwa v[68:69], v240 src0_sel:WORD_1
	v_cvt_pk_f32_fp8_e32 v[70:71], v241
	v_cvt_pk_f32_fp8_sdwa v[72:73], v241 src0_sel:WORD_1
	v_cvt_pk_f32_fp8_e32 v[74:75], v242
	v_cvt_pk_f32_fp8_sdwa v[76:77], v242 src0_sel:WORD_1
	v_cvt_pk_f32_fp8_e32 v[78:79], v243
	v_cvt_pk_f32_fp8_sdwa v[80:81], v243 src0_sel:WORD_1
	v_lshl_add_u32 v11, v114, 10, v8
	v_lshl_add_u32 v65, v115, 10, v8
	global_load_dwordx4 v[236:239], v11, s[6:7]
	global_load_dwordx4 v[240:243], v65, s[6:7]
	v_pk_fma_f32 v[20:21], v[44:45], v[146:147], v[20:21] op_sel_hi:[1,0,1]
	v_pk_fma_f32 v[22:23], v[46:47], v[146:147], v[22:23] op_sel_hi:[1,0,1]
	v_pk_fma_f32 v[24:25], v[48:49], v[146:147], v[24:25] op_sel_hi:[1,0,1]
	v_pk_fma_f32 v[26:27], v[50:51], v[146:147], v[26:27] op_sel_hi:[1,0,1]
	v_pk_fma_f32 v[28:29], v[52:53], v[146:147], v[28:29] op_sel_hi:[1,0,1]
	v_pk_fma_f32 v[30:31], v[54:55], v[146:147], v[30:31] op_sel_hi:[1,0,1]
	v_pk_fma_f32 v[32:33], v[56:57], v[146:147], v[32:33] op_sel_hi:[1,0,1]
	v_pk_fma_f32 v[34:35], v[58:59], v[146:147], v[34:35] op_sel_hi:[1,0,1]
	v_pk_fma_f32 v[20:21], v[66:67], v[146:147], v[20:21] op_sel:[0,1,0]
	v_pk_fma_f32 v[22:23], v[68:69], v[146:147], v[22:23] op_sel:[0,1,0]
	v_pk_fma_f32 v[24:25], v[70:71], v[146:147], v[24:25] op_sel:[0,1,0]
	v_pk_fma_f32 v[26:27], v[72:73], v[146:147], v[26:27] op_sel:[0,1,0]
	v_pk_fma_f32 v[28:29], v[74:75], v[146:147], v[28:29] op_sel:[0,1,0]
	v_pk_fma_f32 v[30:31], v[76:77], v[146:147], v[30:31] op_sel:[0,1,0]
	v_pk_fma_f32 v[32:33], v[78:79], v[146:147], v[32:33] op_sel:[0,1,0]
	v_pk_fma_f32 v[34:35], v[80:81], v[146:147], v[34:35] op_sel:[0,1,0]
	ds_write_b128 v3, v[20:23] offset:0
	ds_write_b128 v3, v[24:27] offset:128
	ds_write_b128 v3, v[28:31] offset:256
	ds_write_b128 v3, v[32:35] offset:384
	ds_read_b64 v[82:83], v4 offset:0
	ds_read_b64 v[84:85], v4 offset:512
	ds_read_b64 v[86:87], v4 offset:1024
	ds_read_b64 v[88:89], v4 offset:1536
	ds_read_b64 v[90:91], v4 offset:2048
	ds_read_b64 v[92:93], v4 offset:2560
	ds_read_b64 v[94:95], v4 offset:3072
	ds_read_b64 v[96:97], v4 offset:3584
	s_waitcnt lgkmcnt(0)
	v_pk_add_f32 v[82:83], v[82:83], v[84:85]
	v_pk_add_f32 v[86:87], v[86:87], v[88:89]
	v_pk_add_f32 v[90:91], v[90:91], v[92:93]
	v_pk_add_f32 v[94:95], v[94:95], v[96:97]
	v_pk_add_f32 v[82:83], v[82:83], v[86:87]
	v_pk_add_f32 v[90:91], v[90:91], v[94:95]
	s_nop 0
	v_pk_add_f32 v[82:83], v[82:83], v[90:91]
	s_nop 0
	global_store_dwordx2 v12, v[82:83], s[58:59]
	s_add_i32 s18, s18, 1
	s_add_i32 s20, s18, 1
	s_min_i32 s20, s20, 0x7f
	s_lshr_b32 s21, s20, 4
	s_and_b32 s22, s20, 15
	s_add_i32 s23, s18, 2
	s_min_i32 s23, s23, 0x7f
	s_and_b32 s24, s23, 15
	s_and_b32 s26, s18, 15
	s_lshr_b32 s27, s18, 4
	s_lshl_b32 s22, s22, 11
	s_lshl_b32 s24, s24, 11
	s_lshl_b32 s28, s21, 7
	s_lshl_b32 s26, s26, 11
	s_lshl_b32 s27, s27, 9
	v_add_u32_e32 v6, s22, v64
	v_add_u32_e32 v7, s24, v64
	v_add_u32_e32 v8, s28, v2
	v_lshl_add_u32 v10, v6, 9, v148
	v_lshl_add_u32 v9, v7, 9, v148
	v_add_u32_e32 v12, s26, v64
	v_lshl_add_u32 v12, v12, 12, v5
	v_add_u32_e32 v12, s27, v12
	s_waitcnt vmcnt(17)
	ds_write_b64 v149, v[152:153]
	ds_write_b64 v149, v[154:155] offset:512
	ds_read_b128 v[100:103], v150 offset:0
	ds_read_b128 v[104:107], v150 offset:16
	ds_read_b128 v[108:111], v150 offset:32
	ds_read_b128 v[112:115], v150 offset:48
	ds_read_b128 v[132:135], v150 offset:512
	ds_read_b128 v[136:139], v150 offset:528
	ds_read_b128 v[140:143], v150 offset:544
	ds_read_b128 v[144:147], v150 offset:560
	global_load_dwordx2 v[152:153], v9, s[2:3]
	global_load_dwordx2 v[154:155], v10, s[8:9]
	s_waitcnt lgkmcnt(0)
	s_waitcnt vmcnt(17)
	v_cvt_pk_f32_fp8_e32 v[44:45], v180
	v_cvt_pk_f32_fp8_sdwa v[46:47], v180 src0_sel:WORD_1
	v_cvt_pk_f32_fp8_e32 v[48:49], v181
	v_cvt_pk_f32_fp8_sdwa v[50:51], v181 src0_sel:WORD_1
	v_cvt_pk_f32_fp8_e32 v[52:53], v182
	v_cvt_pk_f32_fp8_sdwa v[54:55], v182 src0_sel:WORD_1
	v_cvt_pk_f32_fp8_e32 v[56:57], v183
	v_cvt_pk_f32_fp8_sdwa v[58:59], v183 src0_sel:WORD_1
	v_cvt_pk_f32_fp8_e32 v[66:67], v184
	v_cvt_pk_f32_fp8_sdwa v[68:69], v184 src0_sel:WORD_1
	v_cvt_pk_f32_fp8_e32 v[70:71], v185
	v_cvt_pk_f32_fp8_sdwa v[72:73], v185 src0_sel:WORD_1
	v_cvt_pk_f32_fp8_e32 v[74:75], v186
	v_cvt_pk_f32_fp8_sdwa v[76:77], v186 src0_sel:WORD_1
	v_cvt_pk_f32_fp8_e32 v[78:79], v187
	v_cvt_pk_f32_fp8_sdwa v[80:81], v187 src0_sel:WORD_1
	v_lshl_add_u32 v11, v100, 10, v8
	v_lshl_add_u32 v65, v101, 10, v8
	global_load_dwordx4 v[180:183], v11, s[6:7]
	global_load_dwordx4 v[184:187], v65, s[6:7]
	v_pk_mul_f32 v[20:21], v[44:45], v[132:133] op_sel_hi:[1,0]
	v_pk_mul_f32 v[22:23], v[46:47], v[132:133] op_sel_hi:[1,0]
	v_pk_mul_f32 v[24:25], v[48:49], v[132:133] op_sel_hi:[1,0]
	v_pk_mul_f32 v[26:27], v[50:51], v[132:133] op_sel_hi:[1,0]
	v_pk_mul_f32 v[28:29], v[52:53], v[132:133] op_sel_hi:[1,0]
	v_pk_mul_f32 v[30:31], v[54:55], v[132:133] op_sel_hi:[1,0]
	v_pk_mul_f32 v[32:33], v[56:57], v[132:133] op_sel_hi:[1,0]
	v_pk_mul_f32 v[34:35], v[58:59], v[132:133] op_sel_hi:[1,0]
	v_pk_fma_f32 v[20:21], v[66:67], v[132:133], v[20:21] op_sel:[0,1,0]
	v_pk_fma_f32 v[22:23], v[68:69], v[132:133], v[22:23] op_sel:[0,1,0]
	v_pk_fma_f32 v[24:25], v[70:71], v[132:133], v[24:25] op_sel:[0,1,0]
	v_pk_fma_f32 v[26:27], v[72:73], v[132:133], v[26:27] op_sel:[0,1,0]
	v_pk_fma_f32 v[28:29], v[74:75], v[132:133], v[28:29] op_sel:[0,1,0]
	v_pk_fma_f32 v[30:31], v[76:77], v[132:133], v[30:31] op_sel:[0,1,0]
	v_pk_fma_f32 v[32:33], v[78:79], v[132:133], v[32:33] op_sel:[0,1,0]
	v_pk_fma_f32 v[34:35], v[80:81], v[132:133], v[34:35] op_sel:[0,1,0]
	s_waitcnt vmcnt(17)
; DI void phase_peer_ffn(const Params& p) {
;     ...
; #pragma unroll
;       for (int k = 0; k < 16; ++k) {
;         const float ck = __int_as_float(__builtin_amdgcn_readlane(__float_as_int(cv), lbase + k));
; #pragma unroll
;         for (int w = 0; w < 4; ++w) {
;           f2_t lo = __builtin_amdgcn_cvt_pk_f32_fp8((int)ur[k][w], false);
;           f2_t hi = __builtin_amdgcn_cvt_pk_f32_fp8((int)ur[k][w], true);
;           yacc[4 * w] = fmaf(ck, lo[0], yacc[4 * w]);
;           yacc[4 * w + 1] = fmaf(ck, lo[1], yacc[4 * w + 1]);
;           yacc[4 * w + 2] = fmaf(ck, hi[0], yacc[4 * w + 2]);
;           yacc[4 * w + 3] = fmaf(ck, hi[1], yacc[4 * w + 3]);
;         }
;       }
	v_cvt_pk_f32_fp8_e32 v[44:45], v188
	v_cvt_pk_f32_fp8_sdwa v[46:47], v188 src0_sel:WORD_1
	v_cvt_pk_f32_fp8_e32 v[48:49], v189
	v_cvt_pk_f32_fp8_sdwa v[50:51], v189 src0_sel:WORD_1
	v_cvt_pk_f32_fp8_e32 v[52:53], v190
	v_cvt_pk_f32_fp8_sdwa v[54:55], v190 src0_sel:WORD_1
	v_cvt_pk_f32_fp8_e32 v[56:57], v191
	v_cvt_pk_f32_fp8_sdwa v[58:59], v191 src0_sel:WORD_1
	v_cvt_pk_f32_fp8_e32 v[66:67], v192
	v_cvt_pk_f32_fp8_sdwa v[68:69], v192 src0_sel:WORD_1
	v_cvt_pk_f32_fp8_e32 v[70:71], v193
	v_cvt_pk_f32_fp8_sdwa v[72:73], v193 src0_sel:WORD_1
	v_cvt_pk_f32_fp8_e32 v[74:75], v194
	v_cvt_pk_f32_fp8_sdwa v[76:77], v194 src0_sel:WORD_1
	v_cvt_pk_f32_fp8_e32 v[78:79], v195
	v_cvt_pk_f32_fp8_sdwa v[80:81], v195 src0_sel:WORD_1
	v_lshl_add_u32 v11, v102, 10, v8
	v_lshl_add_u32 v65, v103, 10, v8
	global_load_dwordx4 v[188:191], v11, s[6:7]
	global_load_dwordx4 v[192:195], v65, s[6:7]
	v_pk_fma_f32 v[20:21], v[44:45], v[134:135], v[20:21] op_sel_hi:[1,0,1]
	v_pk_fma_f32 v[22:23], v[46:47], v[134:135], v[22:23] op_sel_hi:[1,0,1]
	v_pk_fma_f32 v[24:25], v[48:49], v[134:135], v[24:25] op_sel_hi:[1,0,1]
	v_pk_fma_f32 v[26:27], v[50:51], v[134:135], v[26:27] op_sel_hi:[1,0,1]
	v_pk_fma_f32 v[28:29], v[52:53], v[134:135], v[28:29] op_sel_hi:[1,0,1]
	v_pk_fma_f32 v[30:31], v[54:55], v[134:135], v[30:31] op_sel_hi:[1,0,1]
	v_pk_fma_f32 v[32:33], v[56:57], v[134:135], v[32:33] op_sel_hi:[1,0,1]
	v_pk_fma_f32 v[34:35], v[58:59], v[134:135], v[34:35] op_sel_hi:[1,0,1]
	v_pk_fma_f32 v[20:21], v[66:67], v[134:135], v[20:21] op_sel:[0,1,0]
	v_pk_fma_f32 v[22:23], v[68:69], v[134:135], v[22:23] op_sel:[0,1,0]
	v_pk_fma_f32 v[24:25], v[70:71], v[134:135], v[24:25] op_sel:[0,1,0]
	v_pk_fma_f32 v[26:27], v[72:73], v[134:135], v[26:27] op_sel:[0,1,0]
	v_pk_fma_f32 v[28:29], v[74:75], v[134:135], v[28:29] op_sel:[0,1,0]
	v_pk_fma_f32 v[30:31], v[76:77], v[134:135], v[30:31] op_sel:[0,1,0]
	v_pk_fma_f32 v[32:33], v[78:79], v[134:135], v[32:33] op_sel:[0,1,0]
	v_pk_fma_f32 v[34:35], v[80:81], v[134:135], v[34:35] op_sel:[0,1,0]
	s_waitcnt vmcnt(17)
	v_cvt_pk_f32_fp8_e32 v[44:45], v196
	v_cvt_pk_f32_fp8_sdwa v[46:47], v196 src0_sel:WORD_1
	v_cvt_pk_f32_fp8_e32 v[48:49], v197
	v_cvt_pk_f32_fp8_sdwa v[50:51], v197 src0_sel:WORD_1
	v_cvt_pk_f32_fp8_e32 v[52:53], v198
	v_cvt_pk_f32_fp8_sdwa v[54:55], v198 src0_sel:WORD_1
	v_cvt_pk_f32_fp8_e32 v[56:57], v199
	v_cvt_pk_f32_fp8_sdwa v[58:59], v199 src0_sel:WORD_1
	v_cvt_pk_f32_fp8_e32 v[66:67], v200
	v_cvt_pk_f32_fp8_sdwa v[68:69], v200 src0_sel:WORD_1
	v_cvt_pk_f32_fp8_e32 v[70:71], v201
	v_cvt_pk_f32_fp8_sdwa v[72:73], v201 src0_sel:WORD_1
	v_cvt_pk_f32_fp8_e32 v[74:75], v202
	v_cvt_pk_f32_fp8_sdwa v[76:77], v202 src0_sel:WORD_1
	v_cvt_pk_f32_fp8_e32 v[78:79], v203
	v_cvt_pk_f32_fp8_sdwa v[80:81], v203 src0_sel:WORD_1
	v_lshl_add_u32 v11, v104, 10, v8
	v_lshl_add_u32 v65, v105, 10, v8
	global_load_dwordx4 v[196:199], v11, s[6:7]
	global_load_dwordx4 v[200:203], v65, s[6:7]
	v_pk_fma_f32 v[20:21], v[44:45], v[136:137], v[20:21] op_sel_hi:[1,0,1]
	v_pk_fma_f32 v[22:23], v[46:47], v[136:137], v[22:23] op_sel_hi:[1,0,1]
	v_pk_fma_f32 v[24:25], v[48:49], v[136:137], v[24:25] op_sel_hi:[1,0,1]
	v_pk_fma_f32 v[26:27], v[50:51], v[136:137], v[26:27] op_sel_hi:[1,0,1]
	v_pk_fma_f32 v[28:29], v[52:53], v[136:137], v[28:29] op_sel_hi:[1,0,1]
	v_pk_fma_f32 v[30:31], v[54:55], v[136:137], v[30:31] op_sel_hi:[1,0,1]
	v_pk_fma_f32 v[32:33], v[56:57], v[136:137], v[32:33] op_sel_hi:[1,0,1]
	v_pk_fma_f32 v[34:35], v[58:59], v[136:137], v[34:35] op_sel_hi:[1,0,1]
	v_pk_fma_f32 v[20:21], v[66:67], v[136:137], v[20:21] op_sel:[0,1,0]
	v_pk_fma_f32 v[22:23], v[68:69], v[136:137], v[22:23] op_sel:[0,1,0]
	v_pk_fma_f32 v[24:25], v[70:71], v[136:137], v[24:25] op_sel:[0,1,0]
	v_pk_fma_f32 v[26:27], v[72:73], v[136:137], v[26:27] op_sel:[0,1,0]
	v_pk_fma_f32 v[28:29], v[74:75], v[136:137], v[28:29] op_sel:[0,1,0]
	v_pk_fma_f32 v[30:31], v[76:77], v[136:137], v[30:31] op_sel:[0,1,0]
	v_pk_fma_f32 v[32:33], v[78:79], v[136:137], v[32:33] op_sel:[0,1,0]
	v_pk_fma_f32 v[34:35], v[80:81], v[136:137], v[34:35] op_sel:[0,1,0]
	s_waitcnt vmcnt(17)
	v_cvt_pk_f32_fp8_e32 v[44:45], v204
	v_cvt_pk_f32_fp8_sdwa v[46:47], v204 src0_sel:WORD_1
	v_cvt_pk_f32_fp8_e32 v[48:49], v205
	v_cvt_pk_f32_fp8_sdwa v[50:51], v205 src0_sel:WORD_1
	v_cvt_pk_f32_fp8_e32 v[52:53], v206
	v_cvt_pk_f32_fp8_sdwa v[54:55], v206 src0_sel:WORD_1
	v_cvt_pk_f32_fp8_e32 v[56:57], v207
	v_cvt_pk_f32_fp8_sdwa v[58:59], v207 src0_sel:WORD_1
	v_cvt_pk_f32_fp8_e32 v[66:67], v208
	v_cvt_pk_f32_fp8_sdwa v[68:69], v208 src0_sel:WORD_1
	v_cvt_pk_f32_fp8_e32 v[70:71], v209
	v_cvt_pk_f32_fp8_sdwa v[72:73], v209 src0_sel:WORD_1
	v_cvt_pk_f32_fp8_e32 v[74:75], v210
	v_cvt_pk_f32_fp8_sdwa v[76:77], v210 src0_sel:WORD_1
	v_cvt_pk_f32_fp8_e32 v[78:79], v211
	v_cvt_pk_f32_fp8_sdwa v[80:81], v211 src0_sel:WORD_1
	v_lshl_add_u32 v11, v106, 10, v8
	v_lshl_add_u32 v65, v107, 10, v8
	global_load_dwordx4 v[204:207], v11, s[6:7]
	global_load_dwordx4 v[208:211], v65, s[6:7]
	v_pk_fma_f32 v[20:21], v[44:45], v[138:139], v[20:21] op_sel_hi:[1,0,1]
	v_pk_fma_f32 v[22:23], v[46:47], v[138:139], v[22:23] op_sel_hi:[1,0,1]
	v_pk_fma_f32 v[24:25], v[48:49], v[138:139], v[24:25] op_sel_hi:[1,0,1]
	v_pk_fma_f32 v[26:27], v[50:51], v[138:139], v[26:27] op_sel_hi:[1,0,1]
	v_pk_fma_f32 v[28:29], v[52:53], v[138:139], v[28:29] op_sel_hi:[1,0,1]
	v_pk_fma_f32 v[30:31], v[54:55], v[138:139], v[30:31] op_sel_hi:[1,0,1]
	v_pk_fma_f32 v[32:33], v[56:57], v[138:139], v[32:33] op_sel_hi:[1,0,1]
	v_pk_fma_f32 v[34:35], v[58:59], v[138:139], v[34:35] op_sel_hi:[1,0,1]
	v_pk_fma_f32 v[20:21], v[66:67], v[138:139], v[20:21] op_sel:[0,1,0]
	v_pk_fma_f32 v[22:23], v[68:69], v[138:139], v[22:23] op_sel:[0,1,0]
	v_pk_fma_f32 v[24:25], v[70:71], v[138:139], v[24:25] op_sel:[0,1,0]
	v_pk_fma_f32 v[26:27], v[72:73], v[138:139], v[26:27] op_sel:[0,1,0]
	v_pk_fma_f32 v[28:29], v[74:75], v[138:139], v[28:29] op_sel:[0,1,0]
	v_pk_fma_f32 v[30:31], v[76:77], v[138:139], v[30:31] op_sel:[0,1,0]
	v_pk_fma_f32 v[32:33], v[78:79], v[138:139], v[32:33] op_sel:[0,1,0]
	v_pk_fma_f32 v[34:35], v[80:81], v[138:139], v[34:35] op_sel:[0,1,0]
	s_waitcnt vmcnt(17)
; DI void phase_peer_ffn(const Params& p) {
;     ...
; #pragma unroll
;       for (int k = 0; k < 16; ++k) {
;         const float ck = __int_as_float(__builtin_amdgcn_readlane(__float_as_int(cv), lbase + k));
; #pragma unroll
;         for (int w = 0; w < 4; ++w) {
;           f2_t lo = __builtin_amdgcn_cvt_pk_f32_fp8((int)ur[k][w], false);
;           f2_t hi = __builtin_amdgcn_cvt_pk_f32_fp8((int)ur[k][w], true);
;           yacc[4 * w] = fmaf(ck, lo[0], yacc[4 * w]);
;           yacc[4 * w + 1] = fmaf(ck, lo[1], yacc[4 * w + 1]);
;           yacc[4 * w + 2] = fmaf(ck, hi[0], yacc[4 * w + 2]);
;           yacc[4 * w + 3] = fmaf(ck, hi[1], yacc[4 * w + 3]);
;         }
;       }
	v_cvt_pk_f32_fp8_e32 v[44:45], v212
	v_cvt_pk_f32_fp8_sdwa v[46:47], v212 src0_sel:WORD_1
	v_cvt_pk_f32_fp8_e32 v[48:49], v213
	v_cvt_pk_f32_fp8_sdwa v[50:51], v213 src0_sel:WORD_1
	v_cvt_pk_f32_fp8_e32 v[52:53], v214
	v_cvt_pk_f32_fp8_sdwa v[54:55], v214 src0_sel:WORD_1
	v_cvt_pk_f32_fp8_e32 v[56:57], v215
	v_cvt_pk_f32_fp8_sdwa v[58:59], v215 src0_sel:WORD_1
	v_cvt_pk_f32_fp8_e32 v[66:67], v216
	v_cvt_pk_f32_fp8_sdwa v[68:69], v216 src0_sel:WORD_1
	v_cvt_pk_f32_fp8_e32 v[70:71], v217
	v_cvt_pk_f32_fp8_sdwa v[72:73], v217 src0_sel:WORD_1
	v_cvt_pk_f32_fp8_e32 v[74:75], v218
	v_cvt_pk_f32_fp8_sdwa v[76:77], v218 src0_sel:WORD_1
	v_cvt_pk_f32_fp8_e32 v[78:79], v219
	v_cvt_pk_f32_fp8_sdwa v[80:81], v219 src0_sel:WORD_1
	v_lshl_add_u32 v11, v108, 10, v8
	v_lshl_add_u32 v65, v109, 10, v8
	global_load_dwordx4 v[212:215], v11, s[6:7]
	global_load_dwordx4 v[216:219], v65, s[6:7]
	v_pk_fma_f32 v[20:21], v[44:45], v[140:141], v[20:21] op_sel_hi:[1,0,1]
	v_pk_fma_f32 v[22:23], v[46:47], v[140:141], v[22:23] op_sel_hi:[1,0,1]
	v_pk_fma_f32 v[24:25], v[48:49], v[140:141], v[24:25] op_sel_hi:[1,0,1]
	v_pk_fma_f32 v[26:27], v[50:51], v[140:141], v[26:27] op_sel_hi:[1,0,1]
	v_pk_fma_f32 v[28:29], v[52:53], v[140:141], v[28:29] op_sel_hi:[1,0,1]
	v_pk_fma_f32 v[30:31], v[54:55], v[140:141], v[30:31] op_sel_hi:[1,0,1]
	v_pk_fma_f32 v[32:33], v[56:57], v[140:141], v[32:33] op_sel_hi:[1,0,1]
	v_pk_fma_f32 v[34:35], v[58:59], v[140:141], v[34:35] op_sel_hi:[1,0,1]
	v_pk_fma_f32 v[20:21], v[66:67], v[140:141], v[20:21] op_sel:[0,1,0]
	v_pk_fma_f32 v[22:23], v[68:69], v[140:141], v[22:23] op_sel:[0,1,0]
	v_pk_fma_f32 v[24:25], v[70:71], v[140:141], v[24:25] op_sel:[0,1,0]
	v_pk_fma_f32 v[26:27], v[72:73], v[140:141], v[26:27] op_sel:[0,1,0]
	v_pk_fma_f32 v[28:29], v[74:75], v[140:141], v[28:29] op_sel:[0,1,0]
	v_pk_fma_f32 v[30:31], v[76:77], v[140:141], v[30:31] op_sel:[0,1,0]
	v_pk_fma_f32 v[32:33], v[78:79], v[140:141], v[32:33] op_sel:[0,1,0]
	v_pk_fma_f32 v[34:35], v[80:81], v[140:141], v[34:35] op_sel:[0,1,0]
	s_waitcnt vmcnt(17)
	v_cvt_pk_f32_fp8_e32 v[44:45], v220
	v_cvt_pk_f32_fp8_sdwa v[46:47], v220 src0_sel:WORD_1
	v_cvt_pk_f32_fp8_e32 v[48:49], v221
	v_cvt_pk_f32_fp8_sdwa v[50:51], v221 src0_sel:WORD_1
	v_cvt_pk_f32_fp8_e32 v[52:53], v222
	v_cvt_pk_f32_fp8_sdwa v[54:55], v222 src0_sel:WORD_1
	v_cvt_pk_f32_fp8_e32 v[56:57], v223
	v_cvt_pk_f32_fp8_sdwa v[58:59], v223 src0_sel:WORD_1
	v_cvt_pk_f32_fp8_e32 v[66:67], v224
	v_cvt_pk_f32_fp8_sdwa v[68:69], v224 src0_sel:WORD_1
	v_cvt_pk_f32_fp8_e32 v[70:71], v225
	v_cvt_pk_f32_fp8_sdwa v[72:73], v225 src0_sel:WORD_1
	v_cvt_pk_f32_fp8_e32 v[74:75], v226
	v_cvt_pk_f32_fp8_sdwa v[76:77], v226 src0_sel:WORD_1
	v_cvt_pk_f32_fp8_e32 v[78:79], v227
	v_cvt_pk_f32_fp8_sdwa v[80:81], v227 src0_sel:WORD_1
	v_lshl_add_u32 v11, v110, 10, v8
	v_lshl_add_u32 v65, v111, 10, v8
	global_load_dwordx4 v[220:223], v11, s[6:7]
	global_load_dwordx4 v[224:227], v65, s[6:7]
	v_pk_fma_f32 v[20:21], v[44:45], v[142:143], v[20:21] op_sel_hi:[1,0,1]
	v_pk_fma_f32 v[22:23], v[46:47], v[142:143], v[22:23] op_sel_hi:[1,0,1]
	v_pk_fma_f32 v[24:25], v[48:49], v[142:143], v[24:25] op_sel_hi:[1,0,1]
	v_pk_fma_f32 v[26:27], v[50:51], v[142:143], v[26:27] op_sel_hi:[1,0,1]
	v_pk_fma_f32 v[28:29], v[52:53], v[142:143], v[28:29] op_sel_hi:[1,0,1]
	v_pk_fma_f32 v[30:31], v[54:55], v[142:143], v[30:31] op_sel_hi:[1,0,1]
	v_pk_fma_f32 v[32:33], v[56:57], v[142:143], v[32:33] op_sel_hi:[1,0,1]
	v_pk_fma_f32 v[34:35], v[58:59], v[142:143], v[34:35] op_sel_hi:[1,0,1]
	v_pk_fma_f32 v[20:21], v[66:67], v[142:143], v[20:21] op_sel:[0,1,0]
	v_pk_fma_f32 v[22:23], v[68:69], v[142:143], v[22:23] op_sel:[0,1,0]
	v_pk_fma_f32 v[24:25], v[70:71], v[142:143], v[24:25] op_sel:[0,1,0]
	v_pk_fma_f32 v[26:27], v[72:73], v[142:143], v[26:27] op_sel:[0,1,0]
	v_pk_fma_f32 v[28:29], v[74:75], v[142:143], v[28:29] op_sel:[0,1,0]
	v_pk_fma_f32 v[30:31], v[76:77], v[142:143], v[30:31] op_sel:[0,1,0]
	v_pk_fma_f32 v[32:33], v[78:79], v[142:143], v[32:33] op_sel:[0,1,0]
	v_pk_fma_f32 v[34:35], v[80:81], v[142:143], v[34:35] op_sel:[0,1,0]
	s_waitcnt vmcnt(17)
; DI void phase_peer_ffn(const Params& p) {
;     ...
; #pragma unroll
;       for (int k = 0; k < 16; ++k) {
;         const float ck = __int_as_float(__builtin_amdgcn_readlane(__float_as_int(cv), lbase + k));
; #pragma unroll
;         for (int w = 0; w < 4; ++w) {
;           f2_t lo = __builtin_amdgcn_cvt_pk_f32_fp8((int)ur[k][w], false);
;           f2_t hi = __builtin_amdgcn_cvt_pk_f32_fp8((int)ur[k][w], true);
;           yacc[4 * w] = fmaf(ck, lo[0], yacc[4 * w]);
;           yacc[4 * w + 1] = fmaf(ck, lo[1], yacc[4 * w + 1]);
;           yacc[4 * w + 2] = fmaf(ck, hi[0], yacc[4 * w + 2]);
;           yacc[4 * w + 3] = fmaf(ck, hi[1], yacc[4 * w + 3]);
;         }
;       }
;     ...
;     const float* xr = h + (size_t)tok * 1024 + lane * 16;
;     float v[16];
; #pragma unroll
;     for (int c = 0; c < 4; ++c) {
;       f32x4 t = *reinterpret_cast<const f32x4*>(xr + c * 4);
; #pragma unroll
;       for (int k = 0; k < 4; ++k) v[4 * c + k] = ALPHA * t[k] + yacc[4 * c + k];
;     }
;     float s = 0.f;
; #pragma unroll
;     for (int i = 0; i < 16; ++i) s += v[i];
;     const float mean = wave_sum(s) * (1.f / 1024.f);
;     float q = 0.f;
; #pragma unroll
;     for (int i = 0; i < 16; ++i) { float d = v[i] - mean; q += d * d; }
;     const float rstd = rsqrtf(wave_sum(q) * (1.f / 1024.f) + 1e-5f);
;     float* orow = p.out + (size_t)tok * 1024 + lane * 16;
; #pragma unroll
;     for (int c = 0; c < 4; ++c) {
;       f32x4 gg = *reinterpret_cast<const f32x4*>(p.ln_ffn_g + lane * 16 + c * 4);
;       f32x4 bb = *reinterpret_cast<const f32x4*>(p.ln_ffn_b + lane * 16 + c * 4);
	v_cvt_pk_f32_fp8_e32 v[44:45], v228
	v_cvt_pk_f32_fp8_sdwa v[46:47], v228 src0_sel:WORD_1
	v_cvt_pk_f32_fp8_e32 v[48:49], v229
	v_cvt_pk_f32_fp8_sdwa v[50:51], v229 src0_sel:WORD_1
	v_cvt_pk_f32_fp8_e32 v[52:53], v230
	v_cvt_pk_f32_fp8_sdwa v[54:55], v230 src0_sel:WORD_1
	v_cvt_pk_f32_fp8_e32 v[56:57], v231
	v_cvt_pk_f32_fp8_sdwa v[58:59], v231 src0_sel:WORD_1
	v_cvt_pk_f32_fp8_e32 v[66:67], v232
	v_cvt_pk_f32_fp8_sdwa v[68:69], v232 src0_sel:WORD_1
	v_cvt_pk_f32_fp8_e32 v[70:71], v233
	v_cvt_pk_f32_fp8_sdwa v[72:73], v233 src0_sel:WORD_1
	v_cvt_pk_f32_fp8_e32 v[74:75], v234
	v_cvt_pk_f32_fp8_sdwa v[76:77], v234 src0_sel:WORD_1
	v_cvt_pk_f32_fp8_e32 v[78:79], v235
	v_cvt_pk_f32_fp8_sdwa v[80:81], v235 src0_sel:WORD_1
	v_lshl_add_u32 v11, v112, 10, v8
	v_lshl_add_u32 v65, v113, 10, v8
	global_load_dwordx4 v[228:231], v11, s[6:7]
	global_load_dwordx4 v[232:235], v65, s[6:7]
	v_pk_fma_f32 v[20:21], v[44:45], v[144:145], v[20:21] op_sel_hi:[1,0,1]
	v_pk_fma_f32 v[22:23], v[46:47], v[144:145], v[22:23] op_sel_hi:[1,0,1]
	v_pk_fma_f32 v[24:25], v[48:49], v[144:145], v[24:25] op_sel_hi:[1,0,1]
	v_pk_fma_f32 v[26:27], v[50:51], v[144:145], v[26:27] op_sel_hi:[1,0,1]
	v_pk_fma_f32 v[28:29], v[52:53], v[144:145], v[28:29] op_sel_hi:[1,0,1]
	v_pk_fma_f32 v[30:31], v[54:55], v[144:145], v[30:31] op_sel_hi:[1,0,1]
	v_pk_fma_f32 v[32:33], v[56:57], v[144:145], v[32:33] op_sel_hi:[1,0,1]
	v_pk_fma_f32 v[34:35], v[58:59], v[144:145], v[34:35] op_sel_hi:[1,0,1]
	v_pk_fma_f32 v[20:21], v[66:67], v[144:145], v[20:21] op_sel:[0,1,0]
	v_pk_fma_f32 v[22:23], v[68:69], v[144:145], v[22:23] op_sel:[0,1,0]
	v_pk_fma_f32 v[24:25], v[70:71], v[144:145], v[24:25] op_sel:[0,1,0]
	v_pk_fma_f32 v[26:27], v[72:73], v[144:145], v[26:27] op_sel:[0,1,0]
	v_pk_fma_f32 v[28:29], v[74:75], v[144:145], v[28:29] op_sel:[0,1,0]
	v_pk_fma_f32 v[30:31], v[76:77], v[144:145], v[30:31] op_sel:[0,1,0]
	v_pk_fma_f32 v[32:33], v[78:79], v[144:145], v[32:33] op_sel:[0,1,0]
	v_pk_fma_f32 v[34:35], v[80:81], v[144:145], v[34:35] op_sel:[0,1,0]
	s_waitcnt vmcnt(17)
	v_cvt_pk_f32_fp8_e32 v[44:45], v236
	v_cvt_pk_f32_fp8_sdwa v[46:47], v236 src0_sel:WORD_1
	v_cvt_pk_f32_fp8_e32 v[48:49], v237
	v_cvt_pk_f32_fp8_sdwa v[50:51], v237 src0_sel:WORD_1
	v_cvt_pk_f32_fp8_e32 v[52:53], v238
	v_cvt_pk_f32_fp8_sdwa v[54:55], v238 src0_sel:WORD_1
	v_cvt_pk_f32_fp8_e32 v[56:57], v239
	v_cvt_pk_f32_fp8_sdwa v[58:59], v239 src0_sel:WORD_1
	v_cvt_pk_f32_fp8_e32 v[66:67], v240
	v_cvt_pk_f32_fp8_sdwa v[68:69], v240 src0_sel:WORD_1
	v_cvt_pk_f32_fp8_e32 v[70:71], v241
	v_cvt_pk_f32_fp8_sdwa v[72:73], v241 src0_sel:WORD_1
	v_cvt_pk_f32_fp8_e32 v[74:75], v242
	v_cvt_pk_f32_fp8_sdwa v[76:77], v242 src0_sel:WORD_1
	v_cvt_pk_f32_fp8_e32 v[78:79], v243
	v_cvt_pk_f32_fp8_sdwa v[80:81], v243 src0_sel:WORD_1
	v_lshl_add_u32 v11, v114, 10, v8
	v_lshl_add_u32 v65, v115, 10, v8
	global_load_dwordx4 v[236:239], v11, s[6:7]
	global_load_dwordx4 v[240:243], v65, s[6:7]
	v_pk_fma_f32 v[20:21], v[44:45], v[146:147], v[20:21] op_sel_hi:[1,0,1]
	v_pk_fma_f32 v[22:23], v[46:47], v[146:147], v[22:23] op_sel_hi:[1,0,1]
	v_pk_fma_f32 v[24:25], v[48:49], v[146:147], v[24:25] op_sel_hi:[1,0,1]
	v_pk_fma_f32 v[26:27], v[50:51], v[146:147], v[26:27] op_sel_hi:[1,0,1]
	v_pk_fma_f32 v[28:29], v[52:53], v[146:147], v[28:29] op_sel_hi:[1,0,1]
	v_pk_fma_f32 v[30:31], v[54:55], v[146:147], v[30:31] op_sel_hi:[1,0,1]
	v_pk_fma_f32 v[32:33], v[56:57], v[146:147], v[32:33] op_sel_hi:[1,0,1]
	v_pk_fma_f32 v[34:35], v[58:59], v[146:147], v[34:35] op_sel_hi:[1,0,1]
	v_pk_fma_f32 v[20:21], v[66:67], v[146:147], v[20:21] op_sel:[0,1,0]
	v_pk_fma_f32 v[22:23], v[68:69], v[146:147], v[22:23] op_sel:[0,1,0]
	v_pk_fma_f32 v[24:25], v[70:71], v[146:147], v[24:25] op_sel:[0,1,0]
	v_pk_fma_f32 v[26:27], v[72:73], v[146:147], v[26:27] op_sel:[0,1,0]
	v_pk_fma_f32 v[28:29], v[74:75], v[146:147], v[28:29] op_sel:[0,1,0]
	v_pk_fma_f32 v[30:31], v[76:77], v[146:147], v[30:31] op_sel:[0,1,0]
	v_pk_fma_f32 v[32:33], v[78:79], v[146:147], v[32:33] op_sel:[0,1,0]
	v_pk_fma_f32 v[34:35], v[80:81], v[146:147], v[34:35] op_sel:[0,1,0]
	ds_write_b128 v3, v[20:23] offset:0
	ds_write_b128 v3, v[24:27] offset:128
	ds_write_b128 v3, v[28:31] offset:256
	ds_write_b128 v3, v[32:35] offset:384
	ds_read_b64 v[82:83], v4 offset:0
	ds_read_b64 v[84:85], v4 offset:512
	ds_read_b64 v[86:87], v4 offset:1024
	ds_read_b64 v[88:89], v4 offset:1536
	ds_read_b64 v[90:91], v4 offset:2048
	ds_read_b64 v[92:93], v4 offset:2560
	ds_read_b64 v[94:95], v4 offset:3072
	ds_read_b64 v[96:97], v4 offset:3584
	s_waitcnt lgkmcnt(0)
	v_pk_add_f32 v[82:83], v[82:83], v[84:85]
	v_pk_add_f32 v[86:87], v[86:87], v[88:89]
	v_pk_add_f32 v[90:91], v[90:91], v[92:93]
	v_pk_add_f32 v[94:95], v[94:95], v[96:97]
	v_pk_add_f32 v[82:83], v[82:83], v[86:87]
	v_pk_add_f32 v[90:91], v[90:91], v[94:95]
	s_nop 0
	v_pk_add_f32 v[82:83], v[82:83], v[90:91]
	s_nop 0
	global_store_dwordx2 v12, v[82:83], s[58:59]
	s_add_i32 s18, s18, 1
	s_cmpk_lt_u32 s18, 0x80
	s_cbranch_scc1 .Lpf_loop
	s_waitcnt vmcnt(0) lgkmcnt(0)
	v_lshlrev_b32_e32 v1, 6, v0
	global_load_dwordx4 v[100:103], v1, s[54:55]
	global_load_dwordx4 v[104:107], v1, s[54:55] offset:16
	global_load_dwordx4 v[108:111], v1, s[54:55] offset:32
	global_load_dwordx4 v[112:115], v1, s[54:55] offset:48
	global_load_dwordx4 v[116:119], v1, s[56:57]
	global_load_dwordx4 v[120:123], v1, s[56:57] offset:16
	global_load_dwordx4 v[124:127], v1, s[56:57] offset:32
	global_load_dwordx4 v[128:131], v1, s[56:57] offset:48
	s_mov_b32 s4, 0x3f9837f0
	s_mov_b32 s5, 0
	v_mov_b32_e32 v3, 0x3727c5ac
	s_mov_b32 s18, 0
	s_mov_b32 s19, 0x800
	v_add_u32_e32 v2, s18, v64
	v_lshl_add_u32 v2, v2, 12, v1
	global_load_dwordx4 v[20:23], v2, s[58:59] sc1
	global_load_dwordx4 v[24:27], v2, s[58:59] offset:16 sc1
	global_load_dwordx4 v[28:31], v2, s[58:59] offset:32 sc1
	global_load_dwordx4 v[32:35], v2, s[58:59] offset:48 sc1
	global_load_dwordx4 v[36:39], v2, s[82:83]
	global_load_dwordx4 v[40:43], v2, s[82:83] offset:16
	global_load_dwordx4 v[44:47], v2, s[82:83] offset:32
	global_load_dwordx4 v[48:51], v2, s[82:83] offset:48
